# GEMM K-loops: no s_setprio flips, and the redundant lgkmcnt(0) behind each pre-MFMA barrier removed (the wait in front of the barrier already covers the reads)
# baseline (speedup 1.0000x reference)
; #define PG8_STAGE(bufoff, gbase, voff) do { _Pragma("unroll") for (int _i = 0; _i < 2; ++_i) \
;         __builtin_amdgcn_global_load_lds((const unsigned*)((const char*)(gbase) + (voff)[_i]), (PG8_LAS unsigned*)(lds + (bufoff) + ldsw + _i * 8192), 16, 0, 0); } while (0)
; #define PG8_LDA(dst, b, h) do { _Pragma("unroll") for (int m = 0; m < 4; ++m) _Pragma("unroll") for (int k = 0; k < 2; ++k) dst[m][k] = *(const PG8_LAS bf16x8*)(lds + PG8_SA(b, h) + aoff + m * 2048 + k * 1024); } while (0)
; #define PG8_LDB(dst, b, h) do { _Pragma("unroll") for (int n = 0; n < 2; ++n) _Pragma("unroll") for (int k = 0; k < 2; ++k) dst[n][k] = *(const PG8_LAS bf16x8*)(lds + PG8_SB(b, h) + boff + n * 2048 + k * 1024); } while (0)
; #define PG8_MMA(ai, bj, At, Bt) do { __builtin_amdgcn_s_setprio(1); _Pragma("unroll") for (int m = 0; m < 4; ++m) _Pragma("unroll") for (int n = 0; n < 2; ++n) _Pragma("unroll") for (int k = 0; k < 2; ++k) \
;         acc[ai][bj][m][n] = __builtin_amdgcn_mfma_f32_16x16x32_bf16(Bt[n][k], At[m][k], acc[ai][bj][m][n], 0, 0, 0); __builtin_amdgcn_s_setprio(0); } while (0)
; #define PG8_WAIT_V(n) asm volatile("s_waitcnt vmcnt(" #n ")" ::: "memory")
; #define PG8_WAIT_L(n) asm volatile("s_waitcnt lgkmcnt(" #n ")" ::: "memory")
; template <class Epi, class Sched, bool ALIGN_EPI = false, bool SP2 = false>
; __device__ __forceinline__ void gemm_phase(PG8_LAS unsigned char* lds, const Gemm g, const Sched& S, const Epi& E) {
;     ...
;             const bool last = (t == nt - 2);
;             const char* a1 = cA + (size_t)(t + 1) * kstep;
;             const char* a2 = last ? nA : cA + (size_t)(t + 2) * kstep; const char* b2 = last ? nB : cB + (size_t)(t + 2) * kstep;
;             const char* a3 = a2 + kstep; const char* b3 = b2 + kstep;
;             if (last && has_next) S.a_ready(nxt);
;             if constexpr (SP2) {
;             PG8_LDB(B0, 0, 0); PG8_LDB(B1, 0, 1); PG8_SCHED; PG8_LDA(At, 0, 0); PG8_STAGE(PG8_SA(1, 1), a1 + hstep, voffA);
;             PG8_WAIT_V(8); PG8_WAIT_L(0); PG8_BAR; PG8_MMA(0, 0, At, B0); PG8_MMA(0, 1, At, B1); PG8_BAR; PG8_SCHED;
;             PG8_LDA(At, 0, 1); PG8_STAGE(PG8_SB(0, 0), b2, voffB); PG8_STAGE(PG8_SB(0, 1), b2 + hstepB, voffB); PG8_STAGE(PG8_SA(0, 0), a2, voffA);
;             PG8_WAIT_V(8); PG8_WAIT_L(0); PG8_BAR; PG8_MMA(1, 0, At, B0); PG8_MMA(1, 1, At, B1); PG8_BAR; PG8_SCHED;
.LBB0_170:
	s_add_u32 s9, s70, s46
	s_addc_u32 s10, s71, s47
	s_add_u32 s9, s9, 0x100
	s_addc_u32 s10, s10, 0
	s_add_u32 s11, s93, s46
	s_addc_u32 s12, s94, s47
	s_add_i32 s13, 0, 0x10000
	s_cmpk_eq_i32 s46, 0xf00
	s_cselect_b32 s85, s4, s10
	s_cselect_b32 s84, s5, s9
	s_cselect_b32 s81, s6, s12
	s_cselect_b32 s80, s7, s11
	s_add_i32 s9, 0, 0x14000
	v_add_u32_e32 v160, s13, v139
	v_add_u32_e32 v178, s9, v139
	ds_read_b128 v[148:151], v160
	ds_read_b128 v[152:155], v160 offset:1024
	ds_read_b128 v[156:159], v160 offset:2048
	ds_read_b128 v[160:163], v160 offset:3072
	ds_read_b128 v[166:169], v178
	ds_read_b128 v[170:173], v178 offset:1024
	ds_read_b128 v[174:177], v178 offset:2048
	ds_read_b128 v[178:181], v178 offset:3072
	v_lshl_add_u64 v[194:195], v[144:145], 0, s[46:47]
	s_add_i32 m0, s1, 0xc000
	ds_read_b128 v[182:185], v165
	ds_read_b128 v[206:209], v165 offset:1024
	ds_read_b128 v[210:213], v165 offset:2048
	ds_read_b128 v[214:217], v165 offset:3072
	ds_read_b128 v[218:221], v165 offset:4096
	ds_read_b128 v[236:239], v165 offset:5120
	ds_read_b128 v[240:243], v165 offset:6144
	ds_read_b128 v[244:247], v165 offset:7168
	global_load_lds_dwordx4 v[194:195], off
	v_lshl_add_u64 v[194:195], v[146:147], 0, s[46:47]
	s_add_i32 m0, s1, 0xe000
	s_nop 0
	global_load_lds_dwordx4 v[194:195], off
	s_waitcnt vmcnt(8)
	s_waitcnt lgkmcnt(0)
	s_barrier
	v_mfma_f32_16x16x32_bf16 v[126:129], v[148:151], v[182:185], v[126:129]
	v_mfma_f32_16x16x32_bf16 v[122:125], v[156:159], v[182:185], v[122:125]
	v_mfma_f32_16x16x32_bf16 v[118:121], v[148:151], v[210:213], v[118:121]
	v_mfma_f32_16x16x32_bf16 v[114:117], v[156:159], v[210:213], v[114:117]
	v_mfma_f32_16x16x32_bf16 v[110:113], v[148:151], v[218:221], v[110:113]
	v_mfma_f32_16x16x32_bf16 v[106:109], v[156:159], v[218:221], v[106:109]
	v_mfma_f32_16x16x32_bf16 v[102:105], v[148:151], v[240:243], v[102:105]
	v_mfma_f32_16x16x32_bf16 v[98:101], v[156:159], v[240:243], v[98:101]
	v_mfma_f32_16x16x32_bf16 v[126:129], v[152:155], v[206:209], v[126:129]
	v_mfma_f32_16x16x32_bf16 v[122:125], v[160:163], v[206:209], v[122:125]
	v_mfma_f32_16x16x32_bf16 v[118:121], v[152:155], v[214:217], v[118:121]
	v_mfma_f32_16x16x32_bf16 v[114:117], v[160:163], v[214:217], v[114:117]
	v_mfma_f32_16x16x32_bf16 v[110:113], v[152:155], v[236:239], v[110:113]
	v_mfma_f32_16x16x32_bf16 v[106:109], v[160:163], v[236:239], v[106:109]
	v_mfma_f32_16x16x32_bf16 v[102:105], v[152:155], v[244:247], v[102:105]
	v_mfma_f32_16x16x32_bf16 v[98:101], v[160:163], v[244:247], v[98:101]
	v_mfma_f32_16x16x32_bf16 v[94:97], v[166:169], v[182:185], v[94:97]
	v_mfma_f32_16x16x32_bf16 v[90:93], v[174:177], v[182:185], v[90:93]
	v_mfma_f32_16x16x32_bf16 v[86:89], v[166:169], v[210:213], v[86:89]
	v_mfma_f32_16x16x32_bf16 v[82:85], v[174:177], v[210:213], v[82:85]
	v_mfma_f32_16x16x32_bf16 v[78:81], v[166:169], v[218:221], v[78:81]
	v_mfma_f32_16x16x32_bf16 v[74:77], v[174:177], v[218:221], v[74:77]
	v_mfma_f32_16x16x32_bf16 v[70:73], v[166:169], v[240:243], v[70:73]
	v_mfma_f32_16x16x32_bf16 v[66:69], v[174:177], v[240:243], v[66:69]
	v_mfma_f32_16x16x32_bf16 v[94:97], v[170:173], v[206:209], v[94:97]
	v_mfma_f32_16x16x32_bf16 v[90:93], v[178:181], v[206:209], v[90:93]
	v_mfma_f32_16x16x32_bf16 v[86:89], v[170:173], v[214:217], v[86:89]
	v_mfma_f32_16x16x32_bf16 v[82:85], v[178:181], v[214:217], v[82:85]
	v_mfma_f32_16x16x32_bf16 v[78:81], v[170:173], v[236:239], v[78:81]
	v_mfma_f32_16x16x32_bf16 v[74:77], v[178:181], v[236:239], v[74:77]
	v_mfma_f32_16x16x32_bf16 v[70:73], v[170:173], v[244:247], v[70:73]
	v_mfma_f32_16x16x32_bf16 v[66:69], v[178:181], v[244:247], v[66:69]
	s_barrier
	s_add_i32 s10, s13, s0
	v_lshl_add_u64 v[194:195], s[80:81], 0, v[132:133]
	s_mov_b32 m0, s10
	ds_read_b128 v[182:185], v165 offset:16384
	ds_read_b128 v[206:209], v165 offset:17408
	ds_read_b128 v[210:213], v165 offset:18432
	ds_read_b128 v[214:217], v165 offset:19456
	ds_read_b128 v[218:221], v165 offset:20480
	ds_read_b128 v[236:239], v165 offset:21504
	ds_read_b128 v[240:243], v165 offset:22528
	ds_read_b128 v[244:247], v165 offset:23552
	global_load_lds_dwordx4 v[194:195], off
	s_add_i32 m0, s10, 0x2000
	s_add_u32 s10, s80, 0x20000
	v_lshl_add_u64 v[196:197], s[80:81], 0, v[136:137]
	s_addc_u32 s11, s81, 0
	s_add_i32 s9, s9, s0
	global_load_lds_dwordx4 v[196:197], off
	v_lshl_add_u64 v[222:223], s[10:11], 0, v[132:133]
	s_mov_b32 m0, s9
	v_lshl_add_u64 v[234:235], s[84:85], 0, v[134:135]
	global_load_lds_dwordx4 v[222:223], off
	v_lshl_add_u64 v[222:223], s[10:11], 0, v[136:137]
	s_add_i32 m0, s9, 0x2000
	s_nop 0
	global_load_lds_dwordx4 v[222:223], off
	v_lshl_add_u64 v[222:223], s[84:85], 0, v[130:131]
	s_mov_b32 m0, s1
	s_nop 0
	global_load_lds_dwordx4 v[222:223], off
	s_mov_b32 m0, s25
	s_nop 0
	global_load_lds_dwordx4 v[234:235], off
	s_waitcnt vmcnt(8)
	s_waitcnt lgkmcnt(0)
	s_barrier
; #define PG8_STAGE(bufoff, gbase, voff) do { _Pragma("unroll") for (int _i = 0; _i < 2; ++_i) \
;         __builtin_amdgcn_global_load_lds((const unsigned*)((const char*)(gbase) + (voff)[_i]), (PG8_LAS unsigned*)(lds + (bufoff) + ldsw + _i * 8192), 16, 0, 0); } while (0)
; #define PG8_LDA(dst, b, h) do { _Pragma("unroll") for (int m = 0; m < 4; ++m) _Pragma("unroll") for (int k = 0; k < 2; ++k) dst[m][k] = *(const PG8_LAS bf16x8*)(lds + PG8_SA(b, h) + aoff + m * 2048 + k * 1024); } while (0)
; #define PG8_LDB(dst, b, h) do { _Pragma("unroll") for (int n = 0; n < 2; ++n) _Pragma("unroll") for (int k = 0; k < 2; ++k) dst[n][k] = *(const PG8_LAS bf16x8*)(lds + PG8_SB(b, h) + boff + n * 2048 + k * 1024); } while (0)
; #define PG8_MMA(ai, bj, At, Bt) do { __builtin_amdgcn_s_setprio(1); _Pragma("unroll") for (int m = 0; m < 4; ++m) _Pragma("unroll") for (int n = 0; n < 2; ++n) _Pragma("unroll") for (int k = 0; k < 2; ++k) \
;         acc[ai][bj][m][n] = __builtin_amdgcn_mfma_f32_16x16x32_bf16(Bt[n][k], At[m][k], acc[ai][bj][m][n], 0, 0, 0); __builtin_amdgcn_s_setprio(0); } while (0)
; #define PG8_WAIT_V(n) asm volatile("s_waitcnt vmcnt(" #n ")" ::: "memory")
; #define PG8_WAIT_L(n) asm volatile("s_waitcnt lgkmcnt(" #n ")" ::: "memory")
; #define PG8_BAR __builtin_amdgcn_s_barrier()
; #define PG8_SCHED __builtin_amdgcn_sched_barrier(0)
; template <class Epi, class Sched, bool ALIGN_EPI = false, bool SP2 = false>
; __device__ __forceinline__ void gemm_phase(PG8_LAS unsigned char* lds, const Gemm g, const Sched& S, const Epi& E) {
;     ...
;             PG8_WAIT_V(8); PG8_WAIT_L(0); PG8_BAR; PG8_MMA(1, 0, At, B0); PG8_MMA(1, 1, At, B1); PG8_BAR; PG8_SCHED;
;             PG8_LDB(B0, 1, 0); PG8_LDB(B1, 1, 1); PG8_SCHED; PG8_LDA(At, 1, 0); PG8_STAGE(PG8_SA(0, 1), a2 + hstep, voffA);
;             PG8_WAIT_V(8); PG8_WAIT_L(0); PG8_BAR; PG8_MMA(0, 0, At, B0); PG8_MMA(0, 1, At, B1); PG8_BAR; PG8_SCHED;
	v_mfma_f32_16x16x32_bf16 v[62:65], v[148:151], v[182:185], v[62:65]
	v_mfma_f32_16x16x32_bf16 v[58:61], v[156:159], v[182:185], v[58:61]
	v_mfma_f32_16x16x32_bf16 v[54:57], v[148:151], v[210:213], v[54:57]
	v_mfma_f32_16x16x32_bf16 v[50:53], v[156:159], v[210:213], v[50:53]
	v_mfma_f32_16x16x32_bf16 v[46:49], v[148:151], v[218:221], v[46:49]
	v_mfma_f32_16x16x32_bf16 v[42:45], v[156:159], v[218:221], v[42:45]
	v_mfma_f32_16x16x32_bf16 v[38:41], v[148:151], v[240:243], v[38:41]
	v_mfma_f32_16x16x32_bf16 v[34:37], v[156:159], v[240:243], v[34:37]
	v_mfma_f32_16x16x32_bf16 v[62:65], v[152:155], v[206:209], v[62:65]
	v_mfma_f32_16x16x32_bf16 v[58:61], v[160:163], v[206:209], v[58:61]
	v_mfma_f32_16x16x32_bf16 v[54:57], v[152:155], v[214:217], v[54:57]
	v_mfma_f32_16x16x32_bf16 v[50:53], v[160:163], v[214:217], v[50:53]
	v_mfma_f32_16x16x32_bf16 v[46:49], v[152:155], v[236:239], v[46:49]
	v_mfma_f32_16x16x32_bf16 v[42:45], v[160:163], v[236:239], v[42:45]
	v_mfma_f32_16x16x32_bf16 v[38:41], v[152:155], v[244:247], v[38:41]
	v_mfma_f32_16x16x32_bf16 v[34:37], v[160:163], v[244:247], v[34:37]
	v_mfma_f32_16x16x32_bf16 v[30:33], v[166:169], v[182:185], v[30:33]
	v_mfma_f32_16x16x32_bf16 v[26:29], v[174:177], v[182:185], v[26:29]
	v_mfma_f32_16x16x32_bf16 v[22:25], v[166:169], v[210:213], v[22:25]
	v_mfma_f32_16x16x32_bf16 v[18:21], v[174:177], v[210:213], v[18:21]
	v_mfma_f32_16x16x32_bf16 v[14:17], v[166:169], v[218:221], v[14:17]
	v_mfma_f32_16x16x32_bf16 v[10:13], v[174:177], v[218:221], v[10:13]
	v_mfma_f32_16x16x32_bf16 v[6:9], v[166:169], v[240:243], v[6:9]
	v_mfma_f32_16x16x32_bf16 v[2:5], v[174:177], v[240:243], v[2:5]
	v_mfma_f32_16x16x32_bf16 v[30:33], v[170:173], v[206:209], v[30:33]
	v_mfma_f32_16x16x32_bf16 v[26:29], v[178:181], v[206:209], v[26:29]
	v_mfma_f32_16x16x32_bf16 v[22:25], v[170:173], v[214:217], v[22:25]
	v_mfma_f32_16x16x32_bf16 v[18:21], v[178:181], v[214:217], v[18:21]
	v_mfma_f32_16x16x32_bf16 v[14:17], v[170:173], v[236:239], v[14:17]
	v_mfma_f32_16x16x32_bf16 v[10:13], v[178:181], v[236:239], v[10:13]
	v_mfma_f32_16x16x32_bf16 v[6:9], v[170:173], v[244:247], v[6:9]
	v_mfma_f32_16x16x32_bf16 v[2:5], v[178:181], v[244:247], v[2:5]
	s_barrier
	s_add_i32 s9, 0, 0x18000
	s_add_i32 s12, 0, 0x1c000
	v_add_u32_e32 v160, s9, v139
	v_add_u32_e32 v178, s12, v139
	ds_read_b128 v[148:151], v160
	ds_read_b128 v[152:155], v160 offset:1024
	ds_read_b128 v[156:159], v160 offset:2048
	ds_read_b128 v[160:163], v160 offset:3072
	ds_read_b128 v[166:169], v178
	ds_read_b128 v[170:173], v178 offset:1024
	ds_read_b128 v[174:177], v178 offset:2048
	ds_read_b128 v[178:181], v178 offset:3072
	s_add_u32 s10, s84, 0x80000
	s_addc_u32 s11, s85, 0
	s_mov_b32 m0, s42
	v_lshl_add_u64 v[198:199], s[10:11], 0, v[130:131]
	ds_read_b128 v[182:185], v165 offset:32768
	ds_read_b128 v[206:209], v165 offset:33792
	ds_read_b128 v[210:213], v165 offset:34816
	ds_read_b128 v[214:217], v165 offset:35840
	ds_read_b128 v[218:221], v165 offset:36864
	ds_read_b128 v[236:239], v165 offset:37888
	ds_read_b128 v[240:243], v165 offset:38912
	ds_read_b128 v[244:247], v165 offset:39936
	global_load_lds_dwordx4 v[198:199], off
	v_lshl_add_u64 v[198:199], s[10:11], 0, v[134:135]
	s_mov_b32 m0, s51
	s_nop 0
	global_load_lds_dwordx4 v[198:199], off
	s_waitcnt vmcnt(8)
	s_waitcnt lgkmcnt(0)
	s_barrier
	v_mfma_f32_16x16x32_bf16 v[126:129], v[148:151], v[182:185], v[126:129]
	v_mfma_f32_16x16x32_bf16 v[122:125], v[156:159], v[182:185], v[122:125]
	v_mfma_f32_16x16x32_bf16 v[118:121], v[148:151], v[210:213], v[118:121]
	v_mfma_f32_16x16x32_bf16 v[114:117], v[156:159], v[210:213], v[114:117]
	v_mfma_f32_16x16x32_bf16 v[110:113], v[148:151], v[218:221], v[110:113]
	v_mfma_f32_16x16x32_bf16 v[106:109], v[156:159], v[218:221], v[106:109]
	v_mfma_f32_16x16x32_bf16 v[102:105], v[148:151], v[240:243], v[102:105]
	v_mfma_f32_16x16x32_bf16 v[98:101], v[156:159], v[240:243], v[98:101]
	v_mfma_f32_16x16x32_bf16 v[126:129], v[152:155], v[206:209], v[126:129]
	v_mfma_f32_16x16x32_bf16 v[122:125], v[160:163], v[206:209], v[122:125]
	v_mfma_f32_16x16x32_bf16 v[118:121], v[152:155], v[214:217], v[118:121]
	v_mfma_f32_16x16x32_bf16 v[114:117], v[160:163], v[214:217], v[114:117]
	v_mfma_f32_16x16x32_bf16 v[110:113], v[152:155], v[236:239], v[110:113]
	v_mfma_f32_16x16x32_bf16 v[106:109], v[160:163], v[236:239], v[106:109]
	v_mfma_f32_16x16x32_bf16 v[102:105], v[152:155], v[244:247], v[102:105]
	v_mfma_f32_16x16x32_bf16 v[98:101], v[160:163], v[244:247], v[98:101]
	v_mfma_f32_16x16x32_bf16 v[94:97], v[166:169], v[182:185], v[94:97]
	v_mfma_f32_16x16x32_bf16 v[90:93], v[174:177], v[182:185], v[90:93]
	v_mfma_f32_16x16x32_bf16 v[86:89], v[166:169], v[210:213], v[86:89]
	v_mfma_f32_16x16x32_bf16 v[82:85], v[174:177], v[210:213], v[82:85]
	v_mfma_f32_16x16x32_bf16 v[78:81], v[166:169], v[218:221], v[78:81]
	v_mfma_f32_16x16x32_bf16 v[74:77], v[174:177], v[218:221], v[74:77]
	v_mfma_f32_16x16x32_bf16 v[70:73], v[166:169], v[240:243], v[70:73]
	v_mfma_f32_16x16x32_bf16 v[66:69], v[174:177], v[240:243], v[66:69]
	v_mfma_f32_16x16x32_bf16 v[94:97], v[170:173], v[206:209], v[94:97]
	v_mfma_f32_16x16x32_bf16 v[90:93], v[178:181], v[206:209], v[90:93]
	v_mfma_f32_16x16x32_bf16 v[86:89], v[170:173], v[214:217], v[86:89]
	v_mfma_f32_16x16x32_bf16 v[82:85], v[178:181], v[214:217], v[82:85]
	v_mfma_f32_16x16x32_bf16 v[78:81], v[170:173], v[236:239], v[78:81]
	v_mfma_f32_16x16x32_bf16 v[74:77], v[178:181], v[236:239], v[74:77]
	v_mfma_f32_16x16x32_bf16 v[70:73], v[170:173], v[244:247], v[70:73]
	v_mfma_f32_16x16x32_bf16 v[66:69], v[178:181], v[244:247], v[66:69]
	s_barrier
; #define PG8_STAGE(bufoff, gbase, voff) do { _Pragma("unroll") for (int _i = 0; _i < 2; ++_i) \
;         __builtin_amdgcn_global_load_lds((const unsigned*)((const char*)(gbase) + (voff)[_i]), (PG8_LAS unsigned*)(lds + (bufoff) + ldsw + _i * 8192), 16, 0, 0); } while (0)
; #define PG8_LDA(dst, b, h) do { _Pragma("unroll") for (int m = 0; m < 4; ++m) _Pragma("unroll") for (int k = 0; k < 2; ++k) dst[m][k] = *(const PG8_LAS bf16x8*)(lds + PG8_SA(b, h) + aoff + m * 2048 + k * 1024); } while (0)
; #define PG8_MMA(ai, bj, At, Bt) do { __builtin_amdgcn_s_setprio(1); _Pragma("unroll") for (int m = 0; m < 4; ++m) _Pragma("unroll") for (int n = 0; n < 2; ++n) _Pragma("unroll") for (int k = 0; k < 2; ++k) \
;         acc[ai][bj][m][n] = __builtin_amdgcn_mfma_f32_16x16x32_bf16(Bt[n][k], At[m][k], acc[ai][bj][m][n], 0, 0, 0); __builtin_amdgcn_s_setprio(0); } while (0)
; #define PG8_WAIT_V(n) asm volatile("s_waitcnt vmcnt(" #n ")" ::: "memory")
; #define PG8_WAIT_L(n) asm volatile("s_waitcnt lgkmcnt(" #n ")" ::: "memory")
; #define PG8_BAR __builtin_amdgcn_s_barrier()
; #define PG8_SCHED __builtin_amdgcn_sched_barrier(0)
; template <class Epi, class Sched, bool ALIGN_EPI = false, bool SP2 = false>
; __device__ __forceinline__ void gemm_phase(PG8_LAS unsigned char* lds, const Gemm g, const Sched& S, const Epi& E) {
;     ...
;         for (int t = 0; t < nt; t += 2) {
;             const bool last = (t == nt - 2);
;             const char* a1 = cA + (size_t)(t + 1) * kstep;
;             const char* a2 = last ? nA : cA + (size_t)(t + 2) * kstep; const char* b2 = last ? nB : cB + (size_t)(t + 2) * kstep;
;             const char* a3 = a2 + kstep; const char* b3 = b2 + kstep;
;             if (last && has_next) S.a_ready(nxt);
;     ...
;             PG8_LDA(At, 1, 1); PG8_STAGE(PG8_SB(1, 0), b3, voffB); PG8_STAGE(PG8_SB(1, 1), b3 + hstepB, voffB); PG8_STAGE(PG8_SA(1, 0), a3, voffA);
;             PG8_WAIT_V(8); PG8_WAIT_L(0); PG8_BAR; PG8_MMA(1, 0, At, B0); PG8_MMA(1, 1, At, B1); PG8_BAR; PG8_SCHED;
	s_add_i32 s9, s9, s0
	v_lshl_add_u64 v[194:195], v[194:195], 0, s[60:61]
	s_mov_b32 m0, s9
	ds_read_b128 v[182:185], v165 offset:49152
	ds_read_b128 v[206:209], v165 offset:50176
	ds_read_b128 v[210:213], v165 offset:51200
	ds_read_b128 v[214:217], v165 offset:52224
	ds_read_b128 v[218:221], v165 offset:53248
	ds_read_b128 v[236:239], v165 offset:54272
	ds_read_b128 v[240:243], v165 offset:55296
	ds_read_b128 v[244:247], v165 offset:56320
	global_load_lds_dwordx4 v[194:195], off
	s_add_i32 m0, s9, 0x2000
	s_add_u32 s10, s80, 0x20080
	v_lshl_add_u64 v[194:195], v[196:197], 0, s[60:61]
	s_addc_u32 s11, s81, 0
	s_add_i32 s9, s12, s0
	global_load_lds_dwordx4 v[194:195], off
	v_lshl_add_u64 v[194:195], s[10:11], 0, v[132:133]
	s_mov_b32 m0, s9
	s_nop 0
	global_load_lds_dwordx4 v[194:195], off
	v_lshl_add_u64 v[194:195], s[10:11], 0, v[136:137]
	s_add_i32 m0, s9, 0x2000
	s_nop 0
	global_load_lds_dwordx4 v[194:195], off
	v_lshl_add_u64 v[194:195], v[222:223], 0, s[60:61]
	s_mov_b32 m0, s66
	s_nop 0
	global_load_lds_dwordx4 v[194:195], off
	v_lshl_add_u64 v[194:195], v[234:235], 0, s[60:61]
	s_mov_b32 m0, s67
	s_nop 0
	global_load_lds_dwordx4 v[194:195], off
	s_waitcnt vmcnt(8)
	s_waitcnt lgkmcnt(0)
	s_barrier
	v_mfma_f32_16x16x32_bf16 v[62:65], v[148:151], v[182:185], v[62:65]
	v_mfma_f32_16x16x32_bf16 v[58:61], v[156:159], v[182:185], v[58:61]
	v_mfma_f32_16x16x32_bf16 v[54:57], v[148:151], v[210:213], v[54:57]
	v_mfma_f32_16x16x32_bf16 v[50:53], v[156:159], v[210:213], v[50:53]
	v_mfma_f32_16x16x32_bf16 v[46:49], v[148:151], v[218:221], v[46:49]
	v_mfma_f32_16x16x32_bf16 v[42:45], v[156:159], v[218:221], v[42:45]
	v_mfma_f32_16x16x32_bf16 v[38:41], v[148:151], v[240:243], v[38:41]
	v_mfma_f32_16x16x32_bf16 v[34:37], v[156:159], v[240:243], v[34:37]
	v_mfma_f32_16x16x32_bf16 v[62:65], v[152:155], v[206:209], v[62:65]
	v_mfma_f32_16x16x32_bf16 v[58:61], v[160:163], v[206:209], v[58:61]
	v_mfma_f32_16x16x32_bf16 v[54:57], v[152:155], v[214:217], v[54:57]
	v_mfma_f32_16x16x32_bf16 v[50:53], v[160:163], v[214:217], v[50:53]
	v_mfma_f32_16x16x32_bf16 v[46:49], v[152:155], v[236:239], v[46:49]
	v_mfma_f32_16x16x32_bf16 v[42:45], v[160:163], v[236:239], v[42:45]
	v_mfma_f32_16x16x32_bf16 v[38:41], v[152:155], v[244:247], v[38:41]
	v_mfma_f32_16x16x32_bf16 v[34:37], v[160:163], v[244:247], v[34:37]
	v_mfma_f32_16x16x32_bf16 v[30:33], v[166:169], v[182:185], v[30:33]
	v_mfma_f32_16x16x32_bf16 v[26:29], v[174:177], v[182:185], v[26:29]
	v_mfma_f32_16x16x32_bf16 v[22:25], v[166:169], v[210:213], v[22:25]
	v_mfma_f32_16x16x32_bf16 v[18:21], v[174:177], v[210:213], v[18:21]
	v_mfma_f32_16x16x32_bf16 v[14:17], v[166:169], v[218:221], v[14:17]
	v_mfma_f32_16x16x32_bf16 v[10:13], v[174:177], v[218:221], v[10:13]
	v_mfma_f32_16x16x32_bf16 v[6:9], v[166:169], v[240:243], v[6:9]
	v_mfma_f32_16x16x32_bf16 v[2:5], v[174:177], v[240:243], v[2:5]
	v_mfma_f32_16x16x32_bf16 v[30:33], v[170:173], v[206:209], v[30:33]
	v_mfma_f32_16x16x32_bf16 v[26:29], v[178:181], v[206:209], v[26:29]
	v_mfma_f32_16x16x32_bf16 v[22:25], v[170:173], v[214:217], v[22:25]
	v_mfma_f32_16x16x32_bf16 v[18:21], v[178:181], v[214:217], v[18:21]
	v_mfma_f32_16x16x32_bf16 v[14:17], v[170:173], v[236:239], v[14:17]
	v_mfma_f32_16x16x32_bf16 v[10:13], v[178:181], v[236:239], v[10:13]
	v_mfma_f32_16x16x32_bf16 v[6:9], v[170:173], v[244:247], v[6:9]
	v_mfma_f32_16x16x32_bf16 v[2:5], v[178:181], v[244:247], v[2:5]
	s_barrier
	s_add_i32 s8, s8, 2
	s_add_u32 s46, s46, 0x100
	s_addc_u32 s47, s47, 0
	s_cmp_gt_u32 s8, 29
	s_cbranch_scc0 .LBB0_170
	s_and_b64 vcc, exec, s[54:55]
	s_cbranch_vccz .LBB0_173
	s_barrier

; #define PG8_STAGE(bufoff, gbase, voff) do { _Pragma("unroll") for (int _i = 0; _i < 2; ++_i) \
;         __builtin_amdgcn_global_load_lds((const unsigned*)((const char*)(gbase) + (voff)[_i]), (PG8_LAS unsigned*)(lds + (bufoff) + ldsw + _i * 8192), 16, 0, 0); } while (0)
; #define PG8_LDA(dst, b, h) do { _Pragma("unroll") for (int m = 0; m < 4; ++m) _Pragma("unroll") for (int k = 0; k < 2; ++k) dst[m][k] = *(const PG8_LAS bf16x8*)(lds + PG8_SA(b, h) + aoff + m * 2048 + k * 1024); } while (0)
; #define PG8_LDB(dst, b, h) do { _Pragma("unroll") for (int n = 0; n < 2; ++n) _Pragma("unroll") for (int k = 0; k < 2; ++k) dst[n][k] = *(const PG8_LAS bf16x8*)(lds + PG8_SB(b, h) + boff + n * 2048 + k * 1024); } while (0)
; #define PG8_WAIT_V(n) asm volatile("s_waitcnt vmcnt(" #n ")" ::: "memory")
; template <class Epi, class Sched, bool ALIGN_EPI = false, bool SP2 = false>
; __device__ __forceinline__ void gemm_phase(PG8_LAS unsigned char* lds, const Gemm g, const Sched& S, const Epi& E) {
;     ...
;         const char* nA = has_next ? (const char*)g.A + (size_t)nxt.pm * tstep : cA; const char* nB = has_next ? (const char*)g.Bt + (size_t)nxt.pn * tstep : cB;
;         for (int t = 0; t < nt; t += 2) {
;             const bool last = (t == nt - 2);
;             const char* a1 = cA + (size_t)(t + 1) * kstep;
;             const char* a2 = last ? nA : cA + (size_t)(t + 2) * kstep; const char* b2 = last ? nB : cB + (size_t)(t + 2) * kstep;
;             const char* a3 = a2 + kstep; const char* b3 = b2 + kstep;
;             if (last && has_next) S.a_ready(nxt);
;             if constexpr (SP2) {
;             PG8_LDB(B0, 0, 0); PG8_LDB(B1, 0, 1); PG8_SCHED; PG8_LDA(At, 0, 0); PG8_STAGE(PG8_SA(1, 1), a1 + hstep, voffA);
;             PG8_WAIT_V(8); PG8_WAIT_L(0); PG8_BAR; PG8_MMA(0, 0, At, B0); PG8_MMA(0, 1, At, B1); PG8_BAR; PG8_SCHED;
;             PG8_LDA(At, 0, 1); PG8_STAGE(PG8_SB(0, 0), b2, voffB); PG8_STAGE(PG8_SB(0, 1), b2 + hstepB, voffB); PG8_STAGE(PG8_SA(0, 0), a2, voffA);
;             PG8_WAIT_V(8); PG8_WAIT_L(0); PG8_BAR; PG8_MMA(1, 0, At, B0); PG8_MMA(1, 1, At, B1); PG8_BAR; PG8_SCHED;
;             PG8_LDB(B0, 1, 0); PG8_LDB(B1, 1, 1); PG8_SCHED; PG8_LDA(At, 1, 0); PG8_STAGE(PG8_SA(0, 1), a2 + hstep, voffA);
;             PG8_WAIT_V(8); PG8_WAIT_L(0); PG8_BAR; PG8_MMA(0, 0, At, B0); PG8_MMA(0, 1, At, B1); PG8_BAR; PG8_SCHED;
.LBB0_788:
	s_add_u32 s9, s68, 0xfffe0080
	s_addc_u32 s10, s69, -1
	s_add_i32 s11, 0, 0x10000
	s_cmp_eq_u32 s8, 4
	s_cselect_b32 s77, s36, s10
	s_cselect_b32 s76, s37, s9
	s_cselect_b32 s73, s4, s7
	s_cselect_b32 s72, s5, s6
	s_add_i32 s9, 0, 0x14000
	v_add_u32_e32 v54, s11, v193
	v_add_u32_e32 v150, s9, v193
	ds_read_b128 v[34:37], v54
	ds_read_b128 v[38:41], v54 offset:1024
	ds_read_b128 v[50:53], v54 offset:2048
	ds_read_b128 v[54:57], v54 offset:3072
	ds_read_b128 v[114:117], v150
	ds_read_b128 v[126:129], v150 offset:1024
	ds_read_b128 v[138:141], v150 offset:2048
	ds_read_b128 v[150:153], v150 offset:3072
	v_lshl_add_u64 v[184:185], s[68:69], 0, v[180:181]
	s_add_i32 m0, s66, 0xc000
	ds_read_b128 v[154:157], v217
	ds_read_b128 v[158:161], v217 offset:1024
	ds_read_b128 v[170:173], v217 offset:2048
	ds_read_b128 v[206:209], v217 offset:3072
	ds_read_b128 v[210:213], v217 offset:4096
	ds_read_b128 v[218:221], v217 offset:5120
	ds_read_b128 v[236:239], v217 offset:6144
	ds_read_b128 v[240:243], v217 offset:7168
	global_load_lds_dwordx4 v[184:185], off
	v_lshl_add_u64 v[184:185], s[68:69], 0, v[182:183]
	s_add_i32 m0, s66, 0xe000
	s_nop 0
	global_load_lds_dwordx4 v[184:185], off
	s_waitcnt vmcnt(8)
	s_waitcnt lgkmcnt(0)
	s_barrier
	v_mfma_f32_16x16x32_bf16 v[166:169], v[34:37], v[154:157], v[166:169]
	v_mfma_f32_16x16x32_bf16 v[162:165], v[50:53], v[154:157], v[162:165]
	v_mfma_f32_16x16x32_bf16 v[134:137], v[34:37], v[170:173], v[134:137]
	v_mfma_f32_16x16x32_bf16 v[130:133], v[50:53], v[170:173], v[130:133]
	v_mfma_f32_16x16x32_bf16 v[110:113], v[34:37], v[210:213], v[110:113]
	v_mfma_f32_16x16x32_bf16 v[106:109], v[50:53], v[210:213], v[106:109]
	v_mfma_f32_16x16x32_bf16 v[94:97], v[34:37], v[236:239], v[94:97]
	v_mfma_f32_16x16x32_bf16 v[90:93], v[50:53], v[236:239], v[90:93]
	v_mfma_f32_16x16x32_bf16 v[166:169], v[38:41], v[158:161], v[166:169]
	v_mfma_f32_16x16x32_bf16 v[162:165], v[54:57], v[158:161], v[162:165]
	v_mfma_f32_16x16x32_bf16 v[134:137], v[38:41], v[206:209], v[134:137]
	v_mfma_f32_16x16x32_bf16 v[130:133], v[54:57], v[206:209], v[130:133]
	v_mfma_f32_16x16x32_bf16 v[110:113], v[38:41], v[218:221], v[110:113]
	v_mfma_f32_16x16x32_bf16 v[106:109], v[54:57], v[218:221], v[106:109]
	v_mfma_f32_16x16x32_bf16 v[94:97], v[38:41], v[240:243], v[94:97]
	v_mfma_f32_16x16x32_bf16 v[90:93], v[54:57], v[240:243], v[90:93]
	v_mfma_f32_16x16x32_bf16 v[146:149], v[114:117], v[154:157], v[146:149]
	v_mfma_f32_16x16x32_bf16 v[142:145], v[138:141], v[154:157], v[142:145]
	v_mfma_f32_16x16x32_bf16 v[122:125], v[114:117], v[170:173], v[122:125]
	v_mfma_f32_16x16x32_bf16 v[118:121], v[138:141], v[170:173], v[118:121]
	v_mfma_f32_16x16x32_bf16 v[102:105], v[114:117], v[210:213], v[102:105]
	v_mfma_f32_16x16x32_bf16 v[98:101], v[138:141], v[210:213], v[98:101]
	v_mfma_f32_16x16x32_bf16 v[86:89], v[114:117], v[236:239], v[86:89]
	v_mfma_f32_16x16x32_bf16 v[82:85], v[138:141], v[236:239], v[82:85]
	v_mfma_f32_16x16x32_bf16 v[146:149], v[126:129], v[158:161], v[146:149]
	v_mfma_f32_16x16x32_bf16 v[142:145], v[150:153], v[158:161], v[142:145]
	v_mfma_f32_16x16x32_bf16 v[122:125], v[126:129], v[206:209], v[122:125]
	v_mfma_f32_16x16x32_bf16 v[118:121], v[150:153], v[206:209], v[118:121]
	v_mfma_f32_16x16x32_bf16 v[102:105], v[126:129], v[218:221], v[102:105]
	v_mfma_f32_16x16x32_bf16 v[98:101], v[150:153], v[218:221], v[98:101]
	v_mfma_f32_16x16x32_bf16 v[86:89], v[126:129], v[240:243], v[86:89]
	v_mfma_f32_16x16x32_bf16 v[82:85], v[150:153], v[240:243], v[82:85]
	s_barrier
	s_add_i32 s10, s11, s25
	v_lshl_add_u64 v[184:185], s[72:73], 0, v[190:191]
	s_mov_b32 m0, s10
	ds_read_b128 v[154:157], v217 offset:16384
	ds_read_b128 v[158:161], v217 offset:17408
	ds_read_b128 v[170:173], v217 offset:18432
	ds_read_b128 v[206:209], v217 offset:19456
	ds_read_b128 v[210:213], v217 offset:20480
	ds_read_b128 v[218:221], v217 offset:21504
	ds_read_b128 v[236:239], v217 offset:22528
	ds_read_b128 v[240:243], v217 offset:23552
	global_load_lds_dwordx4 v[184:185], off
	s_add_i32 m0, s10, 0x2000
	s_add_u32 s10, s72, 0x8000
	v_lshl_add_u64 v[194:195], s[72:73], 0, v[174:175]
	s_addc_u32 s11, s73, 0
	s_add_i32 s9, s9, s25
	global_load_lds_dwordx4 v[194:195], off
	v_lshl_add_u64 v[196:197], s[10:11], 0, v[190:191]
	s_mov_b32 m0, s9
	v_lshl_add_u64 v[198:199], s[76:77], 0, v[176:177]
	global_load_lds_dwordx4 v[196:197], off
	v_lshl_add_u64 v[196:197], s[10:11], 0, v[174:175]
	s_add_i32 m0, s9, 0x2000
	s_nop 0
	global_load_lds_dwordx4 v[196:197], off
	v_lshl_add_u64 v[196:197], s[76:77], 0, v[178:179]
	s_mov_b32 m0, s66
	s_nop 0
	global_load_lds_dwordx4 v[196:197], off
	s_mov_b32 m0, s67
	s_nop 0
	global_load_lds_dwordx4 v[198:199], off
	s_waitcnt vmcnt(8)
	s_waitcnt lgkmcnt(0)
	s_barrier
; #define PG8_STAGE(bufoff, gbase, voff) do { _Pragma("unroll") for (int _i = 0; _i < 2; ++_i) \
;         __builtin_amdgcn_global_load_lds((const unsigned*)((const char*)(gbase) + (voff)[_i]), (PG8_LAS unsigned*)(lds + (bufoff) + ldsw + _i * 8192), 16, 0, 0); } while (0)
; #define PG8_LDA(dst, b, h) do { _Pragma("unroll") for (int m = 0; m < 4; ++m) _Pragma("unroll") for (int k = 0; k < 2; ++k) dst[m][k] = *(const PG8_LAS bf16x8*)(lds + PG8_SA(b, h) + aoff + m * 2048 + k * 1024); } while (0)
; #define PG8_LDB(dst, b, h) do { _Pragma("unroll") for (int n = 0; n < 2; ++n) _Pragma("unroll") for (int k = 0; k < 2; ++k) dst[n][k] = *(const PG8_LAS bf16x8*)(lds + PG8_SB(b, h) + boff + n * 2048 + k * 1024); } while (0)
; #define PG8_MMA(ai, bj, At, Bt) do { __builtin_amdgcn_s_setprio(1); _Pragma("unroll") for (int m = 0; m < 4; ++m) _Pragma("unroll") for (int n = 0; n < 2; ++n) _Pragma("unroll") for (int k = 0; k < 2; ++k) \
;         acc[ai][bj][m][n] = __builtin_amdgcn_mfma_f32_16x16x32_bf16(Bt[n][k], At[m][k], acc[ai][bj][m][n], 0, 0, 0); __builtin_amdgcn_s_setprio(0); } while (0)
; #define PG8_WAIT_V(n) asm volatile("s_waitcnt vmcnt(" #n ")" ::: "memory")
; #define PG8_WAIT_L(n) asm volatile("s_waitcnt lgkmcnt(" #n ")" ::: "memory")
; #define PG8_BAR __builtin_amdgcn_s_barrier()
; #define PG8_SCHED __builtin_amdgcn_sched_barrier(0)
; template <class Epi, class Sched, bool ALIGN_EPI = false, bool SP2 = false>
; __device__ __forceinline__ void gemm_phase(PG8_LAS unsigned char* lds, const Gemm g, const Sched& S, const Epi& E) {
;     ...
;             PG8_WAIT_V(8); PG8_WAIT_L(0); PG8_BAR; PG8_MMA(1, 0, At, B0); PG8_MMA(1, 1, At, B1); PG8_BAR; PG8_SCHED;
;             PG8_LDB(B0, 1, 0); PG8_LDB(B1, 1, 1); PG8_SCHED; PG8_LDA(At, 1, 0); PG8_STAGE(PG8_SA(0, 1), a2 + hstep, voffA);
;             PG8_WAIT_V(8); PG8_WAIT_L(0); PG8_BAR; PG8_MMA(0, 0, At, B0); PG8_MMA(0, 1, At, B1); PG8_BAR; PG8_SCHED;
	v_mfma_f32_16x16x32_bf16 v[78:81], v[34:37], v[154:157], v[78:81]
	v_mfma_f32_16x16x32_bf16 v[74:77], v[50:53], v[154:157], v[74:77]
	v_mfma_f32_16x16x32_bf16 v[62:65], v[34:37], v[170:173], v[62:65]
	v_mfma_f32_16x16x32_bf16 v[58:61], v[50:53], v[170:173], v[58:61]
	v_mfma_f32_16x16x32_bf16 v[30:33], v[34:37], v[210:213], v[30:33]
	v_mfma_f32_16x16x32_bf16 v[26:29], v[50:53], v[210:213], v[26:29]
	v_mfma_f32_16x16x32_bf16 v[14:17], v[34:37], v[236:239], v[14:17]
	v_mfma_f32_16x16x32_bf16 v[10:13], v[50:53], v[236:239], v[10:13]
	v_mfma_f32_16x16x32_bf16 v[78:81], v[38:41], v[158:161], v[78:81]
	v_mfma_f32_16x16x32_bf16 v[74:77], v[54:57], v[158:161], v[74:77]
	v_mfma_f32_16x16x32_bf16 v[62:65], v[38:41], v[206:209], v[62:65]
	v_mfma_f32_16x16x32_bf16 v[58:61], v[54:57], v[206:209], v[58:61]
	v_mfma_f32_16x16x32_bf16 v[30:33], v[38:41], v[218:221], v[30:33]
	v_mfma_f32_16x16x32_bf16 v[26:29], v[54:57], v[218:221], v[26:29]
	v_mfma_f32_16x16x32_bf16 v[14:17], v[38:41], v[240:243], v[14:17]
	v_mfma_f32_16x16x32_bf16 v[10:13], v[54:57], v[240:243], v[10:13]
	v_mfma_f32_16x16x32_bf16 v[46:49], v[114:117], v[170:173], v[46:49]
	v_mfma_f32_16x16x32_bf16 v[42:45], v[138:141], v[170:173], v[42:45]
	v_mfma_f32_16x16x32_bf16 v[22:25], v[114:117], v[210:213], v[22:25]
	v_mfma_f32_16x16x32_bf16 v[18:21], v[138:141], v[210:213], v[18:21]
	v_mfma_f32_16x16x32_bf16 v[6:9], v[114:117], v[236:239], v[6:9]
	v_mfma_f32_16x16x32_bf16 v[2:5], v[138:141], v[236:239], v[2:5]
	v_mfma_f32_16x16x32_bf16 v[34:37], v[114:117], v[154:157], v[70:73]
	v_mfma_f32_16x16x32_bf16 v[38:41], v[138:141], v[154:157], v[66:69]
	v_mfma_f32_16x16x32_bf16 v[46:49], v[126:129], v[206:209], v[46:49]
	v_mfma_f32_16x16x32_bf16 v[42:45], v[150:153], v[206:209], v[42:45]
	v_mfma_f32_16x16x32_bf16 v[22:25], v[126:129], v[218:221], v[22:25]
	v_mfma_f32_16x16x32_bf16 v[18:21], v[150:153], v[218:221], v[18:21]
	v_mfma_f32_16x16x32_bf16 v[6:9], v[126:129], v[240:243], v[6:9]
	v_mfma_f32_16x16x32_bf16 v[2:5], v[150:153], v[240:243], v[2:5]
	v_mfma_f32_16x16x32_bf16 v[34:37], v[126:129], v[158:161], v[34:37]
	v_mfma_f32_16x16x32_bf16 v[38:41], v[150:153], v[158:161], v[38:41]
	s_barrier
	s_add_i32 s9, 0, 0x18000
	s_add_i32 s12, 0, 0x1c000
	v_add_u32_e32 v70, s9, v193
	v_add_u32_e32 v150, s12, v193
	ds_read_b128 v[50:53], v70
	ds_read_b128 v[54:57], v70 offset:1024
	ds_read_b128 v[66:69], v70 offset:2048
	ds_read_b128 v[70:73], v70 offset:3072
	ds_read_b128 v[114:117], v150
	ds_read_b128 v[126:129], v150 offset:1024
	ds_read_b128 v[138:141], v150 offset:2048
	ds_read_b128 v[150:153], v150 offset:3072
	s_add_u32 s10, s76, 0x20000
	s_addc_u32 s11, s77, 0
	s_mov_b32 m0, s80
	v_lshl_add_u64 v[214:215], s[10:11], 0, v[178:179]
	ds_read_b128 v[154:157], v217 offset:32768
	ds_read_b128 v[158:161], v217 offset:33792
	ds_read_b128 v[170:173], v217 offset:34816
	ds_read_b128 v[206:209], v217 offset:35840
	ds_read_b128 v[210:213], v217 offset:36864
	ds_read_b128 v[218:221], v217 offset:37888
	ds_read_b128 v[236:239], v217 offset:38912
	ds_read_b128 v[240:243], v217 offset:39936
	global_load_lds_dwordx4 v[214:215], off
	v_lshl_add_u64 v[214:215], s[10:11], 0, v[176:177]
	s_mov_b32 m0, s81
	s_nop 0
	global_load_lds_dwordx4 v[214:215], off
	s_waitcnt vmcnt(8)
	s_waitcnt lgkmcnt(0)
	s_barrier
	v_mfma_f32_16x16x32_bf16 v[166:169], v[50:53], v[154:157], v[166:169]
	v_mfma_f32_16x16x32_bf16 v[162:165], v[66:69], v[154:157], v[162:165]
	v_mfma_f32_16x16x32_bf16 v[134:137], v[50:53], v[170:173], v[134:137]
	v_mfma_f32_16x16x32_bf16 v[130:133], v[66:69], v[170:173], v[130:133]
	v_mfma_f32_16x16x32_bf16 v[110:113], v[50:53], v[210:213], v[110:113]
	v_mfma_f32_16x16x32_bf16 v[106:109], v[66:69], v[210:213], v[106:109]
	v_mfma_f32_16x16x32_bf16 v[94:97], v[50:53], v[236:239], v[94:97]
	v_mfma_f32_16x16x32_bf16 v[90:93], v[66:69], v[236:239], v[90:93]
	v_mfma_f32_16x16x32_bf16 v[166:169], v[54:57], v[158:161], v[166:169]
	v_mfma_f32_16x16x32_bf16 v[162:165], v[70:73], v[158:161], v[162:165]
	v_mfma_f32_16x16x32_bf16 v[134:137], v[54:57], v[206:209], v[134:137]
	v_mfma_f32_16x16x32_bf16 v[130:133], v[70:73], v[206:209], v[130:133]
	v_mfma_f32_16x16x32_bf16 v[110:113], v[54:57], v[218:221], v[110:113]
	v_mfma_f32_16x16x32_bf16 v[106:109], v[70:73], v[218:221], v[106:109]
	v_mfma_f32_16x16x32_bf16 v[94:97], v[54:57], v[240:243], v[94:97]
	v_mfma_f32_16x16x32_bf16 v[90:93], v[70:73], v[240:243], v[90:93]
	v_mfma_f32_16x16x32_bf16 v[146:149], v[114:117], v[154:157], v[146:149]
	v_mfma_f32_16x16x32_bf16 v[142:145], v[138:141], v[154:157], v[142:145]
	v_mfma_f32_16x16x32_bf16 v[122:125], v[114:117], v[170:173], v[122:125]
	v_mfma_f32_16x16x32_bf16 v[118:121], v[138:141], v[170:173], v[118:121]
	v_mfma_f32_16x16x32_bf16 v[102:105], v[114:117], v[210:213], v[102:105]
	v_mfma_f32_16x16x32_bf16 v[98:101], v[138:141], v[210:213], v[98:101]
	v_mfma_f32_16x16x32_bf16 v[86:89], v[114:117], v[236:239], v[86:89]
	v_mfma_f32_16x16x32_bf16 v[82:85], v[138:141], v[236:239], v[82:85]
	v_mfma_f32_16x16x32_bf16 v[146:149], v[126:129], v[158:161], v[146:149]
	v_mfma_f32_16x16x32_bf16 v[142:145], v[150:153], v[158:161], v[142:145]
	v_mfma_f32_16x16x32_bf16 v[122:125], v[126:129], v[206:209], v[122:125]
	v_mfma_f32_16x16x32_bf16 v[118:121], v[150:153], v[206:209], v[118:121]
	v_mfma_f32_16x16x32_bf16 v[102:105], v[126:129], v[218:221], v[102:105]
	v_mfma_f32_16x16x32_bf16 v[98:101], v[150:153], v[218:221], v[98:101]
	v_mfma_f32_16x16x32_bf16 v[86:89], v[126:129], v[240:243], v[86:89]
	v_mfma_f32_16x16x32_bf16 v[82:85], v[150:153], v[240:243], v[82:85]
	s_barrier
; #define PG8_STAGE(bufoff, gbase, voff) do { _Pragma("unroll") for (int _i = 0; _i < 2; ++_i) \
;         __builtin_amdgcn_global_load_lds((const unsigned*)((const char*)(gbase) + (voff)[_i]), (PG8_LAS unsigned*)(lds + (bufoff) + ldsw + _i * 8192), 16, 0, 0); } while (0)
; #define PG8_LDA(dst, b, h) do { _Pragma("unroll") for (int m = 0; m < 4; ++m) _Pragma("unroll") for (int k = 0; k < 2; ++k) dst[m][k] = *(const PG8_LAS bf16x8*)(lds + PG8_SA(b, h) + aoff + m * 2048 + k * 1024); } while (0)
; #define PG8_MMA(ai, bj, At, Bt) do { __builtin_amdgcn_s_setprio(1); _Pragma("unroll") for (int m = 0; m < 4; ++m) _Pragma("unroll") for (int n = 0; n < 2; ++n) _Pragma("unroll") for (int k = 0; k < 2; ++k) \
;         acc[ai][bj][m][n] = __builtin_amdgcn_mfma_f32_16x16x32_bf16(Bt[n][k], At[m][k], acc[ai][bj][m][n], 0, 0, 0); __builtin_amdgcn_s_setprio(0); } while (0)
; #define PG8_WAIT_V(n) asm volatile("s_waitcnt vmcnt(" #n ")" ::: "memory")
; #define PG8_WAIT_L(n) asm volatile("s_waitcnt lgkmcnt(" #n ")" ::: "memory")
; #define PG8_BAR __builtin_amdgcn_s_barrier()
; #define PG8_SCHED __builtin_amdgcn_sched_barrier(0)
; template <class Epi, class Sched, bool ALIGN_EPI = false, bool SP2 = false>
; __device__ __forceinline__ void gemm_phase(PG8_LAS unsigned char* lds, const Gemm g, const Sched& S, const Epi& E) {
;     ...
;             PG8_LDA(At, 1, 1); PG8_STAGE(PG8_SB(1, 0), b3, voffB); PG8_STAGE(PG8_SB(1, 1), b3 + hstepB, voffB); PG8_STAGE(PG8_SA(1, 0), a3, voffA);
;             PG8_WAIT_V(8); PG8_WAIT_L(0); PG8_BAR; PG8_MMA(1, 0, At, B0); PG8_MMA(1, 1, At, B1); PG8_BAR; PG8_SCHED;
;     ...
;         if constexpr (ALIGN_EPI) { if (wr == 0) PG8_BAR; }
	s_add_i32 s9, s9, s25
	v_lshl_add_u64 v[184:185], v[184:185], 0, s[60:61]
	s_mov_b32 m0, s9
	ds_read_b128 v[154:157], v217 offset:49152
	ds_read_b128 v[158:161], v217 offset:50176
	ds_read_b128 v[170:173], v217 offset:51200
	ds_read_b128 v[206:209], v217 offset:52224
	ds_read_b128 v[210:213], v217 offset:53248
	ds_read_b128 v[218:221], v217 offset:54272
	ds_read_b128 v[236:239], v217 offset:55296
	ds_read_b128 v[240:243], v217 offset:56320
	global_load_lds_dwordx4 v[184:185], off
	s_add_i32 m0, s9, 0x2000
	s_add_u32 s10, s72, 0x8080
	v_lshl_add_u64 v[184:185], v[194:195], 0, s[60:61]
	s_addc_u32 s11, s73, 0
	s_add_i32 s9, s12, s25
	global_load_lds_dwordx4 v[184:185], off
	v_lshl_add_u64 v[184:185], s[10:11], 0, v[190:191]
	s_mov_b32 m0, s9
	s_nop 0
	global_load_lds_dwordx4 v[184:185], off
	v_lshl_add_u64 v[184:185], s[10:11], 0, v[174:175]
	s_add_i32 m0, s9, 0x2000
	s_nop 0
	global_load_lds_dwordx4 v[184:185], off
	v_lshl_add_u64 v[184:185], v[196:197], 0, s[60:61]
	s_mov_b32 m0, s82
	s_nop 0
	global_load_lds_dwordx4 v[184:185], off
	v_lshl_add_u64 v[184:185], v[198:199], 0, s[60:61]
	s_mov_b32 m0, s92
	s_nop 0
	global_load_lds_dwordx4 v[184:185], off
	s_waitcnt vmcnt(8)
	s_waitcnt lgkmcnt(0)
	s_barrier
	v_mfma_f32_16x16x32_bf16 v[78:81], v[50:53], v[154:157], v[78:81]
	v_mfma_f32_16x16x32_bf16 v[74:77], v[66:69], v[154:157], v[74:77]
	v_mfma_f32_16x16x32_bf16 v[62:65], v[50:53], v[170:173], v[62:65]
	v_mfma_f32_16x16x32_bf16 v[58:61], v[66:69], v[170:173], v[58:61]
	v_mfma_f32_16x16x32_bf16 v[30:33], v[50:53], v[210:213], v[30:33]
	v_mfma_f32_16x16x32_bf16 v[26:29], v[66:69], v[210:213], v[26:29]
	v_mfma_f32_16x16x32_bf16 v[14:17], v[50:53], v[236:239], v[14:17]
	v_mfma_f32_16x16x32_bf16 v[10:13], v[66:69], v[236:239], v[10:13]
	v_mfma_f32_16x16x32_bf16 v[78:81], v[54:57], v[158:161], v[78:81]
	v_mfma_f32_16x16x32_bf16 v[74:77], v[70:73], v[158:161], v[74:77]
	v_mfma_f32_16x16x32_bf16 v[62:65], v[54:57], v[206:209], v[62:65]
	v_mfma_f32_16x16x32_bf16 v[58:61], v[70:73], v[206:209], v[58:61]
	v_mfma_f32_16x16x32_bf16 v[30:33], v[54:57], v[218:221], v[30:33]
	v_mfma_f32_16x16x32_bf16 v[26:29], v[70:73], v[218:221], v[26:29]
	v_mfma_f32_16x16x32_bf16 v[14:17], v[54:57], v[240:243], v[14:17]
	v_mfma_f32_16x16x32_bf16 v[10:13], v[70:73], v[240:243], v[10:13]
	v_mfma_f32_16x16x32_bf16 v[34:37], v[114:117], v[154:157], v[34:37]
	v_mfma_f32_16x16x32_bf16 v[70:73], v[126:129], v[158:161], v[34:37]
	v_mfma_f32_16x16x32_bf16 v[34:37], v[138:141], v[154:157], v[38:41]
	v_mfma_f32_16x16x32_bf16 v[66:69], v[150:153], v[158:161], v[34:37]
	v_mfma_f32_16x16x32_bf16 v[34:37], v[114:117], v[170:173], v[46:49]
	v_mfma_f32_16x16x32_bf16 v[46:49], v[126:129], v[206:209], v[34:37]
	v_mfma_f32_16x16x32_bf16 v[34:37], v[138:141], v[170:173], v[42:45]
	v_mfma_f32_16x16x32_bf16 v[22:25], v[114:117], v[210:213], v[22:25]
	v_mfma_f32_16x16x32_bf16 v[18:21], v[138:141], v[210:213], v[18:21]
	v_mfma_f32_16x16x32_bf16 v[6:9], v[114:117], v[236:239], v[6:9]
	v_mfma_f32_16x16x32_bf16 v[2:5], v[138:141], v[236:239], v[2:5]
	v_mfma_f32_16x16x32_bf16 v[42:45], v[150:153], v[206:209], v[34:37]
	v_mfma_f32_16x16x32_bf16 v[22:25], v[126:129], v[218:221], v[22:25]
	v_mfma_f32_16x16x32_bf16 v[18:21], v[150:153], v[218:221], v[18:21]
	v_mfma_f32_16x16x32_bf16 v[6:9], v[126:129], v[240:243], v[6:9]
	v_mfma_f32_16x16x32_bf16 v[2:5], v[150:153], v[240:243], v[2:5]
	s_barrier
	s_add_i32 s8, s8, 2
	s_add_u32 s68, s68, 0x100
	s_addc_u32 s69, s69, 0
	s_add_u32 s6, s6, 0x100
	s_addc_u32 s7, s7, 0
	s_cmp_gt_u32 s8, 5
	s_cbranch_scc0 .LBB0_788
	s_and_b64 vcc, exec, s[46:47]
	s_cbranch_vccz .LBB0_791
	s_barrier

; #define PG8_STAGE(bufoff, gbase, voff) do { _Pragma("unroll") for (int _i = 0; _i < 2; ++_i) \
;         __builtin_amdgcn_global_load_lds((const unsigned*)((const char*)(gbase) + (voff)[_i]), (PG8_LAS unsigned*)(lds + (bufoff) + ldsw + _i * 8192), 16, 0, 0); } while (0)
; #define PG8_LDA(dst, b, h) do { _Pragma("unroll") for (int m = 0; m < 4; ++m) _Pragma("unroll") for (int k = 0; k < 2; ++k) dst[m][k] = *(const PG8_LAS bf16x8*)(lds + PG8_SA(b, h) + aoff + m * 2048 + k * 1024); } while (0)
; #define PG8_LDB(dst, b, h) do { _Pragma("unroll") for (int n = 0; n < 2; ++n) _Pragma("unroll") for (int k = 0; k < 2; ++k) dst[n][k] = *(const PG8_LAS bf16x8*)(lds + PG8_SB(b, h) + boff + n * 2048 + k * 1024); } while (0)
; #define PG8_WAIT_V(n) asm volatile("s_waitcnt vmcnt(" #n ")" ::: "memory")
; template <class Epi, class Sched, bool ALIGN_EPI = false, bool SP2 = false>
; __device__ __forceinline__ void gemm_phase(PG8_LAS unsigned char* lds, const Gemm g, const Sched& S, const Epi& E) {
;     ...
;         const char* nA = has_next ? (const char*)g.A + (size_t)nxt.pm * tstep : cA; const char* nB = has_next ? (const char*)g.Bt + (size_t)nxt.pn * tstep : cB;
;         for (int t = 0; t < nt; t += 2) {
;             const bool last = (t == nt - 2);
;             const char* a1 = cA + (size_t)(t + 1) * kstep;
;             const char* a2 = last ? nA : cA + (size_t)(t + 2) * kstep; const char* b2 = last ? nB : cB + (size_t)(t + 2) * kstep;
;             const char* a3 = a2 + kstep; const char* b3 = b2 + kstep;
;             if (last && has_next) S.a_ready(nxt);
;             if constexpr (SP2) {
;             PG8_LDB(B0, 0, 0); PG8_LDB(B1, 0, 1); PG8_SCHED; PG8_LDA(At, 0, 0); PG8_STAGE(PG8_SA(1, 1), a1 + hstep, voffA);
;             PG8_WAIT_V(8); PG8_WAIT_L(0); PG8_BAR; PG8_MMA(0, 0, At, B0); PG8_MMA(0, 1, At, B1); PG8_BAR; PG8_SCHED;
;             PG8_LDA(At, 0, 1); PG8_STAGE(PG8_SB(0, 0), b2, voffB); PG8_STAGE(PG8_SB(0, 1), b2 + hstepB, voffB); PG8_STAGE(PG8_SA(0, 0), a2, voffA);
;             PG8_WAIT_V(8); PG8_WAIT_L(0); PG8_BAR; PG8_MMA(1, 0, At, B0); PG8_MMA(1, 1, At, B1); PG8_BAR; PG8_SCHED;
;             PG8_LDB(B0, 1, 0); PG8_LDB(B1, 1, 1); PG8_SCHED; PG8_LDA(At, 1, 0); PG8_STAGE(PG8_SA(0, 1), a2 + hstep, voffA);
;             PG8_WAIT_V(8); PG8_WAIT_L(0); PG8_BAR; PG8_MMA(0, 0, At, B0); PG8_MMA(0, 1, At, B1); PG8_BAR; PG8_SCHED;
.LBB0_927:
	s_add_u32 s9, s38, 0xfff80080
	s_addc_u32 s10, s39, -1
	s_add_i32 s11, 0, 0x10000
	s_cmp_eq_u32 s8, 28
	s_cselect_b32 s95, s36, s10
	s_cselect_b32 s94, s37, s9
	s_cselect_b32 s47, s4, s7
	s_cselect_b32 s46, s5, s6
	s_add_i32 s9, 0, 0x14000
	v_add_u32_e32 v86, s11, v193
	v_add_u32_e32 v158, s9, v193
	ds_read_b128 v[66:69], v86
	ds_read_b128 v[70:73], v86 offset:1024
	ds_read_b128 v[78:81], v86 offset:2048
	ds_read_b128 v[86:89], v86 offset:3072
	ds_read_b128 v[146:149], v158
	ds_read_b128 v[150:153], v158 offset:1024
	ds_read_b128 v[154:157], v158 offset:2048
	ds_read_b128 v[158:161], v158 offset:3072
	v_lshl_add_u64 v[194:195], s[38:39], 0, v[212:213]
	s_add_i32 m0, s66, 0xc000
	ds_read_b128 v[162:165], v236
	ds_read_b128 v[166:169], v236 offset:1024
	ds_read_b128 v[170:173], v236 offset:2048
	ds_read_b128 v[174:177], v236 offset:3072
	ds_read_b128 v[178:181], v236 offset:4096
	ds_read_b128 v[182:185], v236 offset:5120
	ds_read_b128 v[216:219], v236 offset:6144
	ds_read_b128 v[220:223], v236 offset:7168
	global_load_lds_dwordx4 v[194:195], off
	v_lshl_add_u64 v[194:195], s[38:39], 0, v[214:215]
	s_add_i32 m0, s66, 0xe000
	s_nop 0
	global_load_lds_dwordx4 v[194:195], off
	s_waitcnt vmcnt(8)
	s_waitcnt lgkmcnt(0)
	s_barrier
	v_mfma_f32_16x16x32_bf16 v[142:145], v[66:69], v[162:165], v[142:145]
	v_mfma_f32_16x16x32_bf16 v[138:141], v[78:81], v[162:165], v[138:141]
	v_mfma_f32_16x16x32_bf16 v[126:129], v[66:69], v[170:173], v[126:129]
	v_mfma_f32_16x16x32_bf16 v[122:125], v[78:81], v[170:173], v[122:125]
	v_mfma_f32_16x16x32_bf16 v[110:113], v[66:69], v[178:181], v[110:113]
	v_mfma_f32_16x16x32_bf16 v[106:109], v[78:81], v[178:181], v[106:109]
	v_mfma_f32_16x16x32_bf16 v[94:97], v[66:69], v[216:219], v[94:97]
	v_mfma_f32_16x16x32_bf16 v[90:93], v[78:81], v[216:219], v[90:93]
	v_mfma_f32_16x16x32_bf16 v[142:145], v[70:73], v[166:169], v[142:145]
	v_mfma_f32_16x16x32_bf16 v[138:141], v[86:89], v[166:169], v[138:141]
	v_mfma_f32_16x16x32_bf16 v[126:129], v[70:73], v[174:177], v[126:129]
	v_mfma_f32_16x16x32_bf16 v[122:125], v[86:89], v[174:177], v[122:125]
	v_mfma_f32_16x16x32_bf16 v[110:113], v[70:73], v[182:185], v[110:113]
	v_mfma_f32_16x16x32_bf16 v[106:109], v[86:89], v[182:185], v[106:109]
	v_mfma_f32_16x16x32_bf16 v[94:97], v[70:73], v[220:223], v[94:97]
	v_mfma_f32_16x16x32_bf16 v[90:93], v[86:89], v[220:223], v[90:93]
	v_mfma_f32_16x16x32_bf16 v[134:137], v[146:149], v[162:165], v[134:137]
	v_mfma_f32_16x16x32_bf16 v[130:133], v[154:157], v[162:165], v[130:133]
	v_mfma_f32_16x16x32_bf16 v[118:121], v[146:149], v[170:173], v[118:121]
	v_mfma_f32_16x16x32_bf16 v[114:117], v[154:157], v[170:173], v[114:117]
	v_mfma_f32_16x16x32_bf16 v[102:105], v[146:149], v[178:181], v[102:105]
	v_mfma_f32_16x16x32_bf16 v[98:101], v[154:157], v[178:181], v[98:101]
	v_mfma_f32_16x16x32_bf16 v[82:85], v[146:149], v[216:219], v[82:85]
	v_mfma_f32_16x16x32_bf16 v[74:77], v[154:157], v[216:219], v[74:77]
	v_mfma_f32_16x16x32_bf16 v[134:137], v[150:153], v[166:169], v[134:137]
	v_mfma_f32_16x16x32_bf16 v[130:133], v[158:161], v[166:169], v[130:133]
	v_mfma_f32_16x16x32_bf16 v[118:121], v[150:153], v[174:177], v[118:121]
	v_mfma_f32_16x16x32_bf16 v[114:117], v[158:161], v[174:177], v[114:117]
	v_mfma_f32_16x16x32_bf16 v[102:105], v[150:153], v[182:185], v[102:105]
	v_mfma_f32_16x16x32_bf16 v[98:101], v[158:161], v[182:185], v[98:101]
	v_mfma_f32_16x16x32_bf16 v[82:85], v[150:153], v[220:223], v[82:85]
	v_mfma_f32_16x16x32_bf16 v[74:77], v[158:161], v[220:223], v[74:77]
	s_barrier
	s_add_i32 s10, s11, s25
	v_lshl_add_u64 v[194:195], s[46:47], 0, v[190:191]
	s_mov_b32 m0, s10
	ds_read_b128 v[162:165], v236 offset:16384
	ds_read_b128 v[166:169], v236 offset:17408
	ds_read_b128 v[170:173], v236 offset:18432
	ds_read_b128 v[174:177], v236 offset:19456
	ds_read_b128 v[178:181], v236 offset:20480
	ds_read_b128 v[182:185], v236 offset:21504
	ds_read_b128 v[216:219], v236 offset:22528
	ds_read_b128 v[220:223], v236 offset:23552
	global_load_lds_dwordx4 v[194:195], off
	s_add_i32 m0, s10, 0x2000
	s_add_u32 s10, s46, 0x20000
	v_lshl_add_u64 v[196:197], s[46:47], 0, v[206:207]
	s_addc_u32 s11, s47, 0
	s_add_i32 s9, s9, s25
	global_load_lds_dwordx4 v[196:197], off
	v_lshl_add_u64 v[198:199], s[10:11], 0, v[190:191]
	s_mov_b32 m0, s9
	v_lshl_add_u64 v[238:239], s[94:95], 0, v[208:209]
	global_load_lds_dwordx4 v[198:199], off
	v_lshl_add_u64 v[198:199], s[10:11], 0, v[206:207]
	s_add_i32 m0, s9, 0x2000
	s_nop 0
	global_load_lds_dwordx4 v[198:199], off
	v_lshl_add_u64 v[198:199], s[94:95], 0, v[210:211]
	s_mov_b32 m0, s66
	s_nop 0
	global_load_lds_dwordx4 v[198:199], off
	s_mov_b32 m0, s67
	s_nop 0
	global_load_lds_dwordx4 v[238:239], off
	s_waitcnt vmcnt(8)
	s_waitcnt lgkmcnt(0)
	s_barrier
; #define PG8_STAGE(bufoff, gbase, voff) do { _Pragma("unroll") for (int _i = 0; _i < 2; ++_i) \
;         __builtin_amdgcn_global_load_lds((const unsigned*)((const char*)(gbase) + (voff)[_i]), (PG8_LAS unsigned*)(lds + (bufoff) + ldsw + _i * 8192), 16, 0, 0); } while (0)
; #define PG8_LDA(dst, b, h) do { _Pragma("unroll") for (int m = 0; m < 4; ++m) _Pragma("unroll") for (int k = 0; k < 2; ++k) dst[m][k] = *(const PG8_LAS bf16x8*)(lds + PG8_SA(b, h) + aoff + m * 2048 + k * 1024); } while (0)
; #define PG8_LDB(dst, b, h) do { _Pragma("unroll") for (int n = 0; n < 2; ++n) _Pragma("unroll") for (int k = 0; k < 2; ++k) dst[n][k] = *(const PG8_LAS bf16x8*)(lds + PG8_SB(b, h) + boff + n * 2048 + k * 1024); } while (0)
; #define PG8_MMA(ai, bj, At, Bt) do { __builtin_amdgcn_s_setprio(1); _Pragma("unroll") for (int m = 0; m < 4; ++m) _Pragma("unroll") for (int n = 0; n < 2; ++n) _Pragma("unroll") for (int k = 0; k < 2; ++k) \
;         acc[ai][bj][m][n] = __builtin_amdgcn_mfma_f32_16x16x32_bf16(Bt[n][k], At[m][k], acc[ai][bj][m][n], 0, 0, 0); __builtin_amdgcn_s_setprio(0); } while (0)
; #define PG8_WAIT_V(n) asm volatile("s_waitcnt vmcnt(" #n ")" ::: "memory")
; #define PG8_WAIT_L(n) asm volatile("s_waitcnt lgkmcnt(" #n ")" ::: "memory")
; #define PG8_BAR __builtin_amdgcn_s_barrier()
; #define PG8_SCHED __builtin_amdgcn_sched_barrier(0)
; template <class Epi, class Sched, bool ALIGN_EPI = false, bool SP2 = false>
; __device__ __forceinline__ void gemm_phase(PG8_LAS unsigned char* lds, const Gemm g, const Sched& S, const Epi& E) {
;     ...
;             PG8_WAIT_V(8); PG8_WAIT_L(0); PG8_BAR; PG8_MMA(1, 0, At, B0); PG8_MMA(1, 1, At, B1); PG8_BAR; PG8_SCHED;
;             PG8_LDB(B0, 1, 0); PG8_LDB(B1, 1, 1); PG8_SCHED; PG8_LDA(At, 1, 0); PG8_STAGE(PG8_SA(0, 1), a2 + hstep, voffA);
;             PG8_WAIT_V(8); PG8_WAIT_L(0); PG8_BAR; PG8_MMA(0, 0, At, B0); PG8_MMA(0, 1, At, B1); PG8_BAR; PG8_SCHED;
	v_mfma_f32_16x16x32_bf16 v[62:65], v[66:69], v[162:165], v[62:65]
	v_mfma_f32_16x16x32_bf16 v[58:61], v[78:81], v[162:165], v[58:61]
	v_mfma_f32_16x16x32_bf16 v[46:49], v[66:69], v[170:173], v[46:49]
	v_mfma_f32_16x16x32_bf16 v[42:45], v[78:81], v[170:173], v[42:45]
	v_mfma_f32_16x16x32_bf16 v[30:33], v[66:69], v[178:181], v[30:33]
	v_mfma_f32_16x16x32_bf16 v[26:29], v[78:81], v[178:181], v[26:29]
	v_mfma_f32_16x16x32_bf16 v[14:17], v[66:69], v[216:219], v[14:17]
	v_mfma_f32_16x16x32_bf16 v[10:13], v[78:81], v[216:219], v[10:13]
	v_mfma_f32_16x16x32_bf16 v[62:65], v[70:73], v[166:169], v[62:65]
	v_mfma_f32_16x16x32_bf16 v[58:61], v[86:89], v[166:169], v[58:61]
	v_mfma_f32_16x16x32_bf16 v[46:49], v[70:73], v[174:177], v[46:49]
	v_mfma_f32_16x16x32_bf16 v[42:45], v[86:89], v[174:177], v[42:45]
	v_mfma_f32_16x16x32_bf16 v[30:33], v[70:73], v[182:185], v[30:33]
	v_mfma_f32_16x16x32_bf16 v[26:29], v[86:89], v[182:185], v[26:29]
	v_mfma_f32_16x16x32_bf16 v[14:17], v[70:73], v[220:223], v[14:17]
	v_mfma_f32_16x16x32_bf16 v[10:13], v[86:89], v[220:223], v[10:13]
	v_mfma_f32_16x16x32_bf16 v[54:57], v[146:149], v[162:165], v[54:57]
	v_mfma_f32_16x16x32_bf16 v[50:53], v[154:157], v[162:165], v[50:53]
	v_mfma_f32_16x16x32_bf16 v[38:41], v[146:149], v[170:173], v[38:41]
	v_mfma_f32_16x16x32_bf16 v[34:37], v[154:157], v[170:173], v[34:37]
	v_mfma_f32_16x16x32_bf16 v[22:25], v[146:149], v[178:181], v[22:25]
	v_mfma_f32_16x16x32_bf16 v[18:21], v[154:157], v[178:181], v[18:21]
	v_mfma_f32_16x16x32_bf16 v[6:9], v[146:149], v[216:219], v[6:9]
	v_mfma_f32_16x16x32_bf16 v[2:5], v[154:157], v[216:219], v[2:5]
	v_mfma_f32_16x16x32_bf16 v[54:57], v[150:153], v[166:169], v[54:57]
	v_mfma_f32_16x16x32_bf16 v[50:53], v[158:161], v[166:169], v[50:53]
	v_mfma_f32_16x16x32_bf16 v[38:41], v[150:153], v[174:177], v[38:41]
	v_mfma_f32_16x16x32_bf16 v[34:37], v[158:161], v[174:177], v[34:37]
	v_mfma_f32_16x16x32_bf16 v[22:25], v[150:153], v[182:185], v[22:25]
	v_mfma_f32_16x16x32_bf16 v[18:21], v[158:161], v[182:185], v[18:21]
	v_mfma_f32_16x16x32_bf16 v[6:9], v[150:153], v[220:223], v[6:9]
	v_mfma_f32_16x16x32_bf16 v[2:5], v[158:161], v[220:223], v[2:5]
	s_barrier
	s_add_i32 s9, 0, 0x18000
	s_add_i32 s12, 0, 0x1c000
	v_add_u32_e32 v86, s9, v193
	v_add_u32_e32 v158, s12, v193
	ds_read_b128 v[66:69], v86
	ds_read_b128 v[70:73], v86 offset:1024
	ds_read_b128 v[78:81], v86 offset:2048
	ds_read_b128 v[86:89], v86 offset:3072
	ds_read_b128 v[146:149], v158
	ds_read_b128 v[150:153], v158 offset:1024
	ds_read_b128 v[154:157], v158 offset:2048
	ds_read_b128 v[158:161], v158 offset:3072
	s_add_u32 s10, s94, 0x80000
	s_addc_u32 s11, s95, 0
	s_mov_b32 m0, s59
	v_lshl_add_u64 v[240:241], s[10:11], 0, v[210:211]
	ds_read_b128 v[162:165], v236 offset:32768
	ds_read_b128 v[166:169], v236 offset:33792
	ds_read_b128 v[170:173], v236 offset:34816
	ds_read_b128 v[174:177], v236 offset:35840
	ds_read_b128 v[178:181], v236 offset:36864
	ds_read_b128 v[182:185], v236 offset:37888
	ds_read_b128 v[216:219], v236 offset:38912
	ds_read_b128 v[220:223], v236 offset:39936
	global_load_lds_dwordx4 v[240:241], off
	v_lshl_add_u64 v[240:241], s[10:11], 0, v[208:209]
	s_mov_b32 m0, s74
	s_nop 0
	global_load_lds_dwordx4 v[240:241], off
	s_waitcnt vmcnt(8)
	s_waitcnt lgkmcnt(0)
	s_barrier
	v_mfma_f32_16x16x32_bf16 v[142:145], v[66:69], v[162:165], v[142:145]
	v_mfma_f32_16x16x32_bf16 v[138:141], v[78:81], v[162:165], v[138:141]
	v_mfma_f32_16x16x32_bf16 v[126:129], v[66:69], v[170:173], v[126:129]
	v_mfma_f32_16x16x32_bf16 v[122:125], v[78:81], v[170:173], v[122:125]
	v_mfma_f32_16x16x32_bf16 v[110:113], v[66:69], v[178:181], v[110:113]
	v_mfma_f32_16x16x32_bf16 v[106:109], v[78:81], v[178:181], v[106:109]
	v_mfma_f32_16x16x32_bf16 v[94:97], v[66:69], v[216:219], v[94:97]
	v_mfma_f32_16x16x32_bf16 v[90:93], v[78:81], v[216:219], v[90:93]
	v_mfma_f32_16x16x32_bf16 v[142:145], v[70:73], v[166:169], v[142:145]
	v_mfma_f32_16x16x32_bf16 v[138:141], v[86:89], v[166:169], v[138:141]
	v_mfma_f32_16x16x32_bf16 v[126:129], v[70:73], v[174:177], v[126:129]
	v_mfma_f32_16x16x32_bf16 v[122:125], v[86:89], v[174:177], v[122:125]
	v_mfma_f32_16x16x32_bf16 v[110:113], v[70:73], v[182:185], v[110:113]
	v_mfma_f32_16x16x32_bf16 v[106:109], v[86:89], v[182:185], v[106:109]
	v_mfma_f32_16x16x32_bf16 v[94:97], v[70:73], v[220:223], v[94:97]
	v_mfma_f32_16x16x32_bf16 v[90:93], v[86:89], v[220:223], v[90:93]
	v_mfma_f32_16x16x32_bf16 v[134:137], v[146:149], v[162:165], v[134:137]
	v_mfma_f32_16x16x32_bf16 v[130:133], v[154:157], v[162:165], v[130:133]
	v_mfma_f32_16x16x32_bf16 v[118:121], v[146:149], v[170:173], v[118:121]
	v_mfma_f32_16x16x32_bf16 v[114:117], v[154:157], v[170:173], v[114:117]
	v_mfma_f32_16x16x32_bf16 v[102:105], v[146:149], v[178:181], v[102:105]
	v_mfma_f32_16x16x32_bf16 v[98:101], v[154:157], v[178:181], v[98:101]
	v_mfma_f32_16x16x32_bf16 v[82:85], v[146:149], v[216:219], v[82:85]
	v_mfma_f32_16x16x32_bf16 v[74:77], v[154:157], v[216:219], v[74:77]
	v_mfma_f32_16x16x32_bf16 v[134:137], v[150:153], v[166:169], v[134:137]
	v_mfma_f32_16x16x32_bf16 v[130:133], v[158:161], v[166:169], v[130:133]
	v_mfma_f32_16x16x32_bf16 v[118:121], v[150:153], v[174:177], v[118:121]
	v_mfma_f32_16x16x32_bf16 v[114:117], v[158:161], v[174:177], v[114:117]
	v_mfma_f32_16x16x32_bf16 v[102:105], v[150:153], v[182:185], v[102:105]
	v_mfma_f32_16x16x32_bf16 v[98:101], v[158:161], v[182:185], v[98:101]
	v_mfma_f32_16x16x32_bf16 v[82:85], v[150:153], v[220:223], v[82:85]
	v_mfma_f32_16x16x32_bf16 v[74:77], v[158:161], v[220:223], v[74:77]
	s_barrier
; #define PG8_STAGE(bufoff, gbase, voff) do { _Pragma("unroll") for (int _i = 0; _i < 2; ++_i) \
;         __builtin_amdgcn_global_load_lds((const unsigned*)((const char*)(gbase) + (voff)[_i]), (PG8_LAS unsigned*)(lds + (bufoff) + ldsw + _i * 8192), 16, 0, 0); } while (0)
; #define PG8_LDA(dst, b, h) do { _Pragma("unroll") for (int m = 0; m < 4; ++m) _Pragma("unroll") for (int k = 0; k < 2; ++k) dst[m][k] = *(const PG8_LAS bf16x8*)(lds + PG8_SA(b, h) + aoff + m * 2048 + k * 1024); } while (0)
; #define PG8_MMA(ai, bj, At, Bt) do { __builtin_amdgcn_s_setprio(1); _Pragma("unroll") for (int m = 0; m < 4; ++m) _Pragma("unroll") for (int n = 0; n < 2; ++n) _Pragma("unroll") for (int k = 0; k < 2; ++k) \
;         acc[ai][bj][m][n] = __builtin_amdgcn_mfma_f32_16x16x32_bf16(Bt[n][k], At[m][k], acc[ai][bj][m][n], 0, 0, 0); __builtin_amdgcn_s_setprio(0); } while (0)
; #define PG8_WAIT_V(n) asm volatile("s_waitcnt vmcnt(" #n ")" ::: "memory")
; #define PG8_WAIT_L(n) asm volatile("s_waitcnt lgkmcnt(" #n ")" ::: "memory")
; #define PG8_BAR __builtin_amdgcn_s_barrier()
; #define PG8_SCHED __builtin_amdgcn_sched_barrier(0)
; template <class Epi, class Sched, bool ALIGN_EPI = false, bool SP2 = false>
; __device__ __forceinline__ void gemm_phase(PG8_LAS unsigned char* lds, const Gemm g, const Sched& S, const Epi& E) {
;     ...
;             PG8_LDA(At, 1, 1); PG8_STAGE(PG8_SB(1, 0), b3, voffB); PG8_STAGE(PG8_SB(1, 1), b3 + hstepB, voffB); PG8_STAGE(PG8_SA(1, 0), a3, voffA);
;             PG8_WAIT_V(8); PG8_WAIT_L(0); PG8_BAR; PG8_MMA(1, 0, At, B0); PG8_MMA(1, 1, At, B1); PG8_BAR; PG8_SCHED;
;     ...
;         if constexpr (ALIGN_EPI) { if (wr == 0) PG8_BAR; }
	s_add_i32 s9, s9, s25
	v_lshl_add_u64 v[194:195], v[194:195], 0, s[60:61]
	s_mov_b32 m0, s9
	ds_read_b128 v[162:165], v236 offset:49152
	ds_read_b128 v[166:169], v236 offset:50176
	ds_read_b128 v[170:173], v236 offset:51200
	ds_read_b128 v[174:177], v236 offset:52224
	ds_read_b128 v[178:181], v236 offset:53248
	ds_read_b128 v[182:185], v236 offset:54272
	ds_read_b128 v[216:219], v236 offset:55296
	ds_read_b128 v[220:223], v236 offset:56320
	global_load_lds_dwordx4 v[194:195], off
	s_add_i32 m0, s9, 0x2000
	s_add_u32 s10, s46, 0x20080
	v_lshl_add_u64 v[194:195], v[196:197], 0, s[60:61]
	s_addc_u32 s11, s47, 0
	s_add_i32 s9, s12, s25
	global_load_lds_dwordx4 v[194:195], off
	v_lshl_add_u64 v[194:195], s[10:11], 0, v[190:191]
	s_mov_b32 m0, s9
	s_nop 0
	global_load_lds_dwordx4 v[194:195], off
	v_lshl_add_u64 v[194:195], s[10:11], 0, v[206:207]
	s_add_i32 m0, s9, 0x2000
	s_nop 0
	global_load_lds_dwordx4 v[194:195], off
	v_lshl_add_u64 v[194:195], v[198:199], 0, s[60:61]
	s_mov_b32 m0, s75
	s_nop 0
	global_load_lds_dwordx4 v[194:195], off
	v_lshl_add_u64 v[194:195], v[238:239], 0, s[60:61]
	s_mov_b32 m0, s0
	s_nop 0
	global_load_lds_dwordx4 v[194:195], off
	s_waitcnt vmcnt(8)
	s_waitcnt lgkmcnt(0)
	s_barrier
	v_mfma_f32_16x16x32_bf16 v[62:65], v[66:69], v[162:165], v[62:65]
	v_mfma_f32_16x16x32_bf16 v[58:61], v[78:81], v[162:165], v[58:61]
	v_mfma_f32_16x16x32_bf16 v[46:49], v[66:69], v[170:173], v[46:49]
	v_mfma_f32_16x16x32_bf16 v[42:45], v[78:81], v[170:173], v[42:45]
	v_mfma_f32_16x16x32_bf16 v[30:33], v[66:69], v[178:181], v[30:33]
	v_mfma_f32_16x16x32_bf16 v[26:29], v[78:81], v[178:181], v[26:29]
	v_mfma_f32_16x16x32_bf16 v[14:17], v[66:69], v[216:219], v[14:17]
	v_mfma_f32_16x16x32_bf16 v[10:13], v[78:81], v[216:219], v[10:13]
	v_mfma_f32_16x16x32_bf16 v[62:65], v[70:73], v[166:169], v[62:65]
	v_mfma_f32_16x16x32_bf16 v[58:61], v[86:89], v[166:169], v[58:61]
	v_mfma_f32_16x16x32_bf16 v[46:49], v[70:73], v[174:177], v[46:49]
	v_mfma_f32_16x16x32_bf16 v[42:45], v[86:89], v[174:177], v[42:45]
	v_mfma_f32_16x16x32_bf16 v[30:33], v[70:73], v[182:185], v[30:33]
	v_mfma_f32_16x16x32_bf16 v[26:29], v[86:89], v[182:185], v[26:29]
	v_mfma_f32_16x16x32_bf16 v[14:17], v[70:73], v[220:223], v[14:17]
	v_mfma_f32_16x16x32_bf16 v[10:13], v[86:89], v[220:223], v[10:13]
	v_mfma_f32_16x16x32_bf16 v[54:57], v[146:149], v[162:165], v[54:57]
	v_mfma_f32_16x16x32_bf16 v[50:53], v[154:157], v[162:165], v[50:53]
	v_mfma_f32_16x16x32_bf16 v[38:41], v[146:149], v[170:173], v[38:41]
	v_mfma_f32_16x16x32_bf16 v[34:37], v[154:157], v[170:173], v[34:37]
	v_mfma_f32_16x16x32_bf16 v[22:25], v[146:149], v[178:181], v[22:25]
	v_mfma_f32_16x16x32_bf16 v[18:21], v[154:157], v[178:181], v[18:21]
	v_mfma_f32_16x16x32_bf16 v[6:9], v[146:149], v[216:219], v[6:9]
	v_mfma_f32_16x16x32_bf16 v[2:5], v[154:157], v[216:219], v[2:5]
	v_mfma_f32_16x16x32_bf16 v[54:57], v[150:153], v[166:169], v[54:57]
	v_mfma_f32_16x16x32_bf16 v[50:53], v[158:161], v[166:169], v[50:53]
	v_mfma_f32_16x16x32_bf16 v[38:41], v[150:153], v[174:177], v[38:41]
	v_mfma_f32_16x16x32_bf16 v[34:37], v[158:161], v[174:177], v[34:37]
	v_mfma_f32_16x16x32_bf16 v[22:25], v[150:153], v[182:185], v[22:25]
	v_mfma_f32_16x16x32_bf16 v[18:21], v[158:161], v[182:185], v[18:21]
	v_mfma_f32_16x16x32_bf16 v[6:9], v[150:153], v[220:223], v[6:9]
	v_mfma_f32_16x16x32_bf16 v[2:5], v[158:161], v[220:223], v[2:5]
	s_barrier
	s_add_i32 s8, s8, 2
	s_add_u32 s38, s38, 0x100
	s_addc_u32 s39, s39, 0
	s_add_u32 s6, s6, 0x100
	s_addc_u32 s7, s7, 0
	s_cmp_gt_u32 s8, 29
	s_cbranch_scc0 .LBB0_927
	s_and_b64 vcc, exec, s[70:71]
	s_cbranch_vccz .LBB0_930
	s_barrier

; #define PG8_STAGE(bufoff, gbase, voff) do { _Pragma("unroll") for (int _i = 0; _i < 2; ++_i) \
;         __builtin_amdgcn_global_load_lds((const unsigned*)((const char*)(gbase) + (voff)[_i]), (PG8_LAS unsigned*)(lds + (bufoff) + ldsw + _i * 8192), 16, 0, 0); } while (0)
; #define PG8_LDA(dst, b, h) do { _Pragma("unroll") for (int m = 0; m < 4; ++m) _Pragma("unroll") for (int k = 0; k < 2; ++k) dst[m][k] = *(const PG8_LAS bf16x8*)(lds + PG8_SA(b, h) + aoff + m * 2048 + k * 1024); } while (0)
; #define PG8_LDB(dst, b, h) do { _Pragma("unroll") for (int n = 0; n < 2; ++n) _Pragma("unroll") for (int k = 0; k < 2; ++k) dst[n][k] = *(const PG8_LAS bf16x8*)(lds + PG8_SB(b, h) + boff + n * 2048 + k * 1024); } while (0)
; #define PG8_WAIT_V(n) asm volatile("s_waitcnt vmcnt(" #n ")" ::: "memory")
; template <class Epi, class Sched, bool ALIGN_EPI = false, bool SP2 = false>
; __device__ __forceinline__ void gemm_phase(PG8_LAS unsigned char* lds, const Gemm g, const Sched& S, const Epi& E) {
;     ...
;         const char* nA = has_next ? (const char*)g.A + (size_t)nxt.pm * tstep : cA; const char* nB = has_next ? (const char*)g.Bt + (size_t)nxt.pn * tstep : cB;
;         for (int t = 0; t < nt; t += 2) {
;             const bool last = (t == nt - 2);
;             const char* a1 = cA + (size_t)(t + 1) * kstep;
;             const char* a2 = last ? nA : cA + (size_t)(t + 2) * kstep; const char* b2 = last ? nB : cB + (size_t)(t + 2) * kstep;
;             const char* a3 = a2 + kstep; const char* b3 = b2 + kstep;
;             if (last && has_next) S.a_ready(nxt);
;             if constexpr (SP2) {
;             PG8_LDB(B0, 0, 0); PG8_LDB(B1, 0, 1); PG8_SCHED; PG8_LDA(At, 0, 0); PG8_STAGE(PG8_SA(1, 1), a1 + hstep, voffA);
;             PG8_WAIT_V(8); PG8_WAIT_L(0); PG8_BAR; PG8_MMA(0, 0, At, B0); PG8_MMA(0, 1, At, B1); PG8_BAR; PG8_SCHED;
;             PG8_LDA(At, 0, 1); PG8_STAGE(PG8_SB(0, 0), b2, voffB); PG8_STAGE(PG8_SB(0, 1), b2 + hstepB, voffB); PG8_STAGE(PG8_SA(0, 0), a2, voffA);
;             PG8_WAIT_V(8); PG8_WAIT_L(0); PG8_BAR; PG8_MMA(1, 0, At, B0); PG8_MMA(1, 1, At, B1); PG8_BAR; PG8_SCHED;
;             PG8_LDB(B0, 1, 0); PG8_LDB(B1, 1, 1); PG8_SCHED; PG8_LDA(At, 1, 0); PG8_STAGE(PG8_SA(0, 1), a2 + hstep, voffA);
;             PG8_WAIT_V(8); PG8_WAIT_L(0); PG8_BAR; PG8_MMA(0, 0, At, B0); PG8_MMA(0, 1, At, B1); PG8_BAR; PG8_SCHED;
.LBB0_1071:
	s_add_u32 s10, s38, 0xffe00080
	s_addc_u32 s11, s39, -1
	s_add_i32 s12, 0, 0x10000
	s_cmpk_eq_i32 s9, 0x7c
	s_cselect_b32 vcc_hi, s97, s11
	s_cselect_b32 vcc_lo, s4, s10
	s_cselect_b32 s47, s5, s8
	s_cselect_b32 s46, s6, s7
	s_add_i32 s13, 0, 0x14000
	v_add_u32_e32 v152, s12, v164
	v_add_u32_e32 v167, s13, v164
	ds_read_b128 v[130:133], v152
	ds_read_b128 v[134:137], v152 offset:1024
	ds_read_b128 v[138:141], v152 offset:2048
	ds_read_b128 v[152:155], v152 offset:3072
	ds_read_b128 v[156:159], v167
	ds_read_b128 v[160:163], v167 offset:1024
	ds_read_b128 v[168:171], v167 offset:2048
	ds_read_b128 v[172:175], v167 offset:3072
	v_lshl_add_u64 v[184:185], s[38:39], 0, v[148:149]
	s_add_i32 m0, s74, 0xc000
	ds_read_b128 v[176:179], v166
	ds_read_b128 v[180:183], v166 offset:1024
	ds_read_b128 v[206:209], v166 offset:2048
	ds_read_b128 v[210:213], v166 offset:3072
	ds_read_b128 v[214:217], v166 offset:4096
	ds_read_b128 v[218:221], v166 offset:5120
	ds_read_b128 v[236:239], v166 offset:6144
	ds_read_b128 v[240:243], v166 offset:7168
	global_load_lds_dwordx4 v[184:185], off
	v_lshl_add_u64 v[184:185], s[38:39], 0, v[150:151]
	s_add_i32 m0, s74, 0xe000
	s_nop 0
	global_load_lds_dwordx4 v[184:185], off
	s_waitcnt vmcnt(8)
	s_waitcnt lgkmcnt(0)
	s_barrier
	v_mfma_f32_16x16x32_bf16 v[126:129], v[130:133], v[176:179], v[126:129]
	v_mfma_f32_16x16x32_bf16 v[122:125], v[138:141], v[176:179], v[122:125]
	v_mfma_f32_16x16x32_bf16 v[110:113], v[130:133], v[206:209], v[110:113]
	v_mfma_f32_16x16x32_bf16 v[106:109], v[138:141], v[206:209], v[106:109]
	v_mfma_f32_16x16x32_bf16 v[94:97], v[130:133], v[214:217], v[94:97]
	v_mfma_f32_16x16x32_bf16 v[90:93], v[138:141], v[214:217], v[90:93]
	v_mfma_f32_16x16x32_bf16 v[78:81], v[130:133], v[236:239], v[78:81]
	v_mfma_f32_16x16x32_bf16 v[74:77], v[138:141], v[236:239], v[74:77]
	v_mfma_f32_16x16x32_bf16 v[126:129], v[134:137], v[180:183], v[126:129]
	v_mfma_f32_16x16x32_bf16 v[122:125], v[152:155], v[180:183], v[122:125]
	v_mfma_f32_16x16x32_bf16 v[110:113], v[134:137], v[210:213], v[110:113]
	v_mfma_f32_16x16x32_bf16 v[106:109], v[152:155], v[210:213], v[106:109]
	v_mfma_f32_16x16x32_bf16 v[94:97], v[134:137], v[218:221], v[94:97]
	v_mfma_f32_16x16x32_bf16 v[90:93], v[152:155], v[218:221], v[90:93]
	v_mfma_f32_16x16x32_bf16 v[78:81], v[134:137], v[240:243], v[78:81]
	v_mfma_f32_16x16x32_bf16 v[74:77], v[152:155], v[240:243], v[74:77]
	v_mfma_f32_16x16x32_bf16 v[118:121], v[156:159], v[176:179], v[118:121]
	v_mfma_f32_16x16x32_bf16 v[114:117], v[168:171], v[176:179], v[114:117]
	v_mfma_f32_16x16x32_bf16 v[102:105], v[156:159], v[206:209], v[102:105]
	v_mfma_f32_16x16x32_bf16 v[98:101], v[168:171], v[206:209], v[98:101]
	v_mfma_f32_16x16x32_bf16 v[86:89], v[156:159], v[214:217], v[86:89]
	v_mfma_f32_16x16x32_bf16 v[82:85], v[168:171], v[214:217], v[82:85]
	v_mfma_f32_16x16x32_bf16 v[70:73], v[156:159], v[236:239], v[70:73]
	v_mfma_f32_16x16x32_bf16 v[66:69], v[168:171], v[236:239], v[66:69]
	v_mfma_f32_16x16x32_bf16 v[118:121], v[160:163], v[180:183], v[118:121]
	v_mfma_f32_16x16x32_bf16 v[114:117], v[172:175], v[180:183], v[114:117]
	v_mfma_f32_16x16x32_bf16 v[102:105], v[160:163], v[210:213], v[102:105]
	v_mfma_f32_16x16x32_bf16 v[98:101], v[172:175], v[210:213], v[98:101]
	v_mfma_f32_16x16x32_bf16 v[86:89], v[160:163], v[218:221], v[86:89]
	v_mfma_f32_16x16x32_bf16 v[82:85], v[172:175], v[218:221], v[82:85]
	v_mfma_f32_16x16x32_bf16 v[70:73], v[160:163], v[240:243], v[70:73]
	v_mfma_f32_16x16x32_bf16 v[66:69], v[172:175], v[240:243], v[66:69]
	s_barrier
	s_add_i32 s10, s12, s67
	v_lshl_add_u64 v[184:185], s[46:47], 0, v[146:147]
	s_mov_b32 m0, s10
	ds_read_b128 v[176:179], v166 offset:16384
	ds_read_b128 v[180:183], v166 offset:17408
	ds_read_b128 v[206:209], v166 offset:18432
	ds_read_b128 v[210:213], v166 offset:19456
	ds_read_b128 v[214:217], v166 offset:20480
	ds_read_b128 v[218:221], v166 offset:21504
	ds_read_b128 v[236:239], v166 offset:22528
	ds_read_b128 v[240:243], v166 offset:23552
	global_load_lds_dwordx4 v[184:185], off
	s_add_i32 m0, s10, 0x2000
	s_add_u32 s10, s46, 0x80000
	v_lshl_add_u64 v[194:195], s[46:47], 0, v[142:143]
	s_addc_u32 s11, s47, 0
	s_add_i32 s12, s13, s67
	global_load_lds_dwordx4 v[194:195], off
	v_lshl_add_u64 v[196:197], s[10:11], 0, v[146:147]
	s_mov_b32 m0, s12
	v_lshl_add_u64 v[198:199], vcc, 0, v[144:145]
	global_load_lds_dwordx4 v[196:197], off
	v_lshl_add_u64 v[196:197], s[10:11], 0, v[142:143]
	s_add_i32 m0, s12, 0x2000
	s_nop 0
	global_load_lds_dwordx4 v[196:197], off
	v_lshl_add_u64 v[196:197], vcc, 0, v[190:191]
	s_mov_b32 m0, s74
	s_nop 0
	global_load_lds_dwordx4 v[196:197], off
	s_mov_b32 m0, s75
	s_nop 0
	global_load_lds_dwordx4 v[198:199], off
	s_waitcnt vmcnt(8)
	s_waitcnt lgkmcnt(0)
	s_barrier
; #define PG8_STAGE(bufoff, gbase, voff) do { _Pragma("unroll") for (int _i = 0; _i < 2; ++_i) \
;         __builtin_amdgcn_global_load_lds((const unsigned*)((const char*)(gbase) + (voff)[_i]), (PG8_LAS unsigned*)(lds + (bufoff) + ldsw + _i * 8192), 16, 0, 0); } while (0)
; #define PG8_LDA(dst, b, h) do { _Pragma("unroll") for (int m = 0; m < 4; ++m) _Pragma("unroll") for (int k = 0; k < 2; ++k) dst[m][k] = *(const PG8_LAS bf16x8*)(lds + PG8_SA(b, h) + aoff + m * 2048 + k * 1024); } while (0)
; #define PG8_LDB(dst, b, h) do { _Pragma("unroll") for (int n = 0; n < 2; ++n) _Pragma("unroll") for (int k = 0; k < 2; ++k) dst[n][k] = *(const PG8_LAS bf16x8*)(lds + PG8_SB(b, h) + boff + n * 2048 + k * 1024); } while (0)
; #define PG8_MMA(ai, bj, At, Bt) do { __builtin_amdgcn_s_setprio(1); _Pragma("unroll") for (int m = 0; m < 4; ++m) _Pragma("unroll") for (int n = 0; n < 2; ++n) _Pragma("unroll") for (int k = 0; k < 2; ++k) \
;         acc[ai][bj][m][n] = __builtin_amdgcn_mfma_f32_16x16x32_bf16(Bt[n][k], At[m][k], acc[ai][bj][m][n], 0, 0, 0); __builtin_amdgcn_s_setprio(0); } while (0)
; #define PG8_WAIT_V(n) asm volatile("s_waitcnt vmcnt(" #n ")" ::: "memory")
; #define PG8_WAIT_L(n) asm volatile("s_waitcnt lgkmcnt(" #n ")" ::: "memory")
; #define PG8_BAR __builtin_amdgcn_s_barrier()
; #define PG8_SCHED __builtin_amdgcn_sched_barrier(0)
; template <class Epi, class Sched, bool ALIGN_EPI = false, bool SP2 = false>
; __device__ __forceinline__ void gemm_phase(PG8_LAS unsigned char* lds, const Gemm g, const Sched& S, const Epi& E) {
;     ...
;             PG8_WAIT_V(8); PG8_WAIT_L(0); PG8_BAR; PG8_MMA(1, 0, At, B0); PG8_MMA(1, 1, At, B1); PG8_BAR; PG8_SCHED;
;             PG8_LDB(B0, 1, 0); PG8_LDB(B1, 1, 1); PG8_SCHED; PG8_LDA(At, 1, 0); PG8_STAGE(PG8_SA(0, 1), a2 + hstep, voffA);
;             PG8_WAIT_V(8); PG8_WAIT_L(0); PG8_BAR; PG8_MMA(0, 0, At, B0); PG8_MMA(0, 1, At, B1); PG8_BAR; PG8_SCHED;
	v_mfma_f32_16x16x32_bf16 v[62:65], v[130:133], v[176:179], v[62:65]
	v_mfma_f32_16x16x32_bf16 v[58:61], v[138:141], v[176:179], v[58:61]
	v_mfma_f32_16x16x32_bf16 v[46:49], v[130:133], v[206:209], v[46:49]
	v_mfma_f32_16x16x32_bf16 v[42:45], v[138:141], v[206:209], v[42:45]
	v_mfma_f32_16x16x32_bf16 v[30:33], v[130:133], v[214:217], v[30:33]
	v_mfma_f32_16x16x32_bf16 v[26:29], v[138:141], v[214:217], v[26:29]
	v_mfma_f32_16x16x32_bf16 v[14:17], v[130:133], v[236:239], v[14:17]
	v_mfma_f32_16x16x32_bf16 v[10:13], v[138:141], v[236:239], v[10:13]
	v_mfma_f32_16x16x32_bf16 v[62:65], v[134:137], v[180:183], v[62:65]
	v_mfma_f32_16x16x32_bf16 v[58:61], v[152:155], v[180:183], v[58:61]
	v_mfma_f32_16x16x32_bf16 v[46:49], v[134:137], v[210:213], v[46:49]
	v_mfma_f32_16x16x32_bf16 v[42:45], v[152:155], v[210:213], v[42:45]
	v_mfma_f32_16x16x32_bf16 v[30:33], v[134:137], v[218:221], v[30:33]
	v_mfma_f32_16x16x32_bf16 v[26:29], v[152:155], v[218:221], v[26:29]
	v_mfma_f32_16x16x32_bf16 v[14:17], v[134:137], v[240:243], v[14:17]
	v_mfma_f32_16x16x32_bf16 v[10:13], v[152:155], v[240:243], v[10:13]
	v_mfma_f32_16x16x32_bf16 v[54:57], v[156:159], v[176:179], v[54:57]
	v_mfma_f32_16x16x32_bf16 v[50:53], v[168:171], v[176:179], v[50:53]
	v_mfma_f32_16x16x32_bf16 v[38:41], v[156:159], v[206:209], v[38:41]
	v_mfma_f32_16x16x32_bf16 v[34:37], v[168:171], v[206:209], v[34:37]
	v_mfma_f32_16x16x32_bf16 v[22:25], v[156:159], v[214:217], v[22:25]
	v_mfma_f32_16x16x32_bf16 v[18:21], v[168:171], v[214:217], v[18:21]
	v_mfma_f32_16x16x32_bf16 v[6:9], v[156:159], v[236:239], v[6:9]
	v_mfma_f32_16x16x32_bf16 v[2:5], v[168:171], v[236:239], v[2:5]
	v_mfma_f32_16x16x32_bf16 v[54:57], v[160:163], v[180:183], v[54:57]
	v_mfma_f32_16x16x32_bf16 v[50:53], v[172:175], v[180:183], v[50:53]
	v_mfma_f32_16x16x32_bf16 v[38:41], v[160:163], v[210:213], v[38:41]
	v_mfma_f32_16x16x32_bf16 v[34:37], v[172:175], v[210:213], v[34:37]
	v_mfma_f32_16x16x32_bf16 v[22:25], v[160:163], v[218:221], v[22:25]
	v_mfma_f32_16x16x32_bf16 v[18:21], v[172:175], v[218:221], v[18:21]
	v_mfma_f32_16x16x32_bf16 v[6:9], v[160:163], v[240:243], v[6:9]
	v_mfma_f32_16x16x32_bf16 v[2:5], v[172:175], v[240:243], v[2:5]
	s_barrier
	s_add_i32 s12, 0, 0x18000
	s_add_i32 s13, 0, 0x1c000
	v_add_u32_e32 v152, s12, v164
	v_add_u32_e32 v167, s13, v164
	ds_read_b128 v[130:133], v152
	ds_read_b128 v[134:137], v152 offset:1024
	ds_read_b128 v[138:141], v152 offset:2048
	ds_read_b128 v[152:155], v152 offset:3072
	ds_read_b128 v[156:159], v167
	ds_read_b128 v[160:163], v167 offset:1024
	ds_read_b128 v[168:171], v167 offset:2048
	ds_read_b128 v[172:175], v167 offset:3072
	s_add_u32 s10, vcc_lo, 0x200000
	s_addc_u32 s11, vcc_hi, 0
	s_mov_b32 m0, s86
	v_lshl_add_u64 v[222:223], s[10:11], 0, v[190:191]
	ds_read_b128 v[176:179], v166 offset:32768
	ds_read_b128 v[180:183], v166 offset:33792
	ds_read_b128 v[206:209], v166 offset:34816
	ds_read_b128 v[210:213], v166 offset:35840
	ds_read_b128 v[214:217], v166 offset:36864
	ds_read_b128 v[218:221], v166 offset:37888
	ds_read_b128 v[236:239], v166 offset:38912
	ds_read_b128 v[240:243], v166 offset:39936
	global_load_lds_dwordx4 v[222:223], off
	v_lshl_add_u64 v[222:223], s[10:11], 0, v[144:145]
	s_mov_b32 m0, s87
	s_nop 0
	global_load_lds_dwordx4 v[222:223], off
	s_waitcnt vmcnt(8)
	s_waitcnt lgkmcnt(0)
	s_barrier
	v_mfma_f32_16x16x32_bf16 v[126:129], v[130:133], v[176:179], v[126:129]
	v_mfma_f32_16x16x32_bf16 v[122:125], v[138:141], v[176:179], v[122:125]
	v_mfma_f32_16x16x32_bf16 v[110:113], v[130:133], v[206:209], v[110:113]
	v_mfma_f32_16x16x32_bf16 v[106:109], v[138:141], v[206:209], v[106:109]
	v_mfma_f32_16x16x32_bf16 v[94:97], v[130:133], v[214:217], v[94:97]
	v_mfma_f32_16x16x32_bf16 v[90:93], v[138:141], v[214:217], v[90:93]
	v_mfma_f32_16x16x32_bf16 v[78:81], v[130:133], v[236:239], v[78:81]
	v_mfma_f32_16x16x32_bf16 v[74:77], v[138:141], v[236:239], v[74:77]
	v_mfma_f32_16x16x32_bf16 v[126:129], v[134:137], v[180:183], v[126:129]
	v_mfma_f32_16x16x32_bf16 v[122:125], v[152:155], v[180:183], v[122:125]
	v_mfma_f32_16x16x32_bf16 v[110:113], v[134:137], v[210:213], v[110:113]
	v_mfma_f32_16x16x32_bf16 v[106:109], v[152:155], v[210:213], v[106:109]
	v_mfma_f32_16x16x32_bf16 v[94:97], v[134:137], v[218:221], v[94:97]
	v_mfma_f32_16x16x32_bf16 v[90:93], v[152:155], v[218:221], v[90:93]
	v_mfma_f32_16x16x32_bf16 v[78:81], v[134:137], v[240:243], v[78:81]
	v_mfma_f32_16x16x32_bf16 v[74:77], v[152:155], v[240:243], v[74:77]
	v_mfma_f32_16x16x32_bf16 v[118:121], v[156:159], v[176:179], v[118:121]
	v_mfma_f32_16x16x32_bf16 v[114:117], v[168:171], v[176:179], v[114:117]
	v_mfma_f32_16x16x32_bf16 v[102:105], v[156:159], v[206:209], v[102:105]
	v_mfma_f32_16x16x32_bf16 v[98:101], v[168:171], v[206:209], v[98:101]
	v_mfma_f32_16x16x32_bf16 v[86:89], v[156:159], v[214:217], v[86:89]
	v_mfma_f32_16x16x32_bf16 v[82:85], v[168:171], v[214:217], v[82:85]
	v_mfma_f32_16x16x32_bf16 v[70:73], v[156:159], v[236:239], v[70:73]
	v_mfma_f32_16x16x32_bf16 v[66:69], v[168:171], v[236:239], v[66:69]
	v_mfma_f32_16x16x32_bf16 v[118:121], v[160:163], v[180:183], v[118:121]
	v_mfma_f32_16x16x32_bf16 v[114:117], v[172:175], v[180:183], v[114:117]
	v_mfma_f32_16x16x32_bf16 v[102:105], v[160:163], v[210:213], v[102:105]
	v_mfma_f32_16x16x32_bf16 v[98:101], v[172:175], v[210:213], v[98:101]
	v_mfma_f32_16x16x32_bf16 v[86:89], v[160:163], v[218:221], v[86:89]
	v_mfma_f32_16x16x32_bf16 v[82:85], v[172:175], v[218:221], v[82:85]
	v_mfma_f32_16x16x32_bf16 v[70:73], v[160:163], v[240:243], v[70:73]
	v_mfma_f32_16x16x32_bf16 v[66:69], v[172:175], v[240:243], v[66:69]
	s_barrier
; #define PG8_STAGE(bufoff, gbase, voff) do { _Pragma("unroll") for (int _i = 0; _i < 2; ++_i) \
;         __builtin_amdgcn_global_load_lds((const unsigned*)((const char*)(gbase) + (voff)[_i]), (PG8_LAS unsigned*)(lds + (bufoff) + ldsw + _i * 8192), 16, 0, 0); } while (0)
; #define PG8_LDA(dst, b, h) do { _Pragma("unroll") for (int m = 0; m < 4; ++m) _Pragma("unroll") for (int k = 0; k < 2; ++k) dst[m][k] = *(const PG8_LAS bf16x8*)(lds + PG8_SA(b, h) + aoff + m * 2048 + k * 1024); } while (0)
; #define PG8_MMA(ai, bj, At, Bt) do { __builtin_amdgcn_s_setprio(1); _Pragma("unroll") for (int m = 0; m < 4; ++m) _Pragma("unroll") for (int n = 0; n < 2; ++n) _Pragma("unroll") for (int k = 0; k < 2; ++k) \
;         acc[ai][bj][m][n] = __builtin_amdgcn_mfma_f32_16x16x32_bf16(Bt[n][k], At[m][k], acc[ai][bj][m][n], 0, 0, 0); __builtin_amdgcn_s_setprio(0); } while (0)
; #define PG8_WAIT_V(n) asm volatile("s_waitcnt vmcnt(" #n ")" ::: "memory")
; #define PG8_WAIT_L(n) asm volatile("s_waitcnt lgkmcnt(" #n ")" ::: "memory")
; #define PG8_BAR __builtin_amdgcn_s_barrier()
; #define PG8_SCHED __builtin_amdgcn_sched_barrier(0)
; template <class Epi, class Sched, bool ALIGN_EPI = false, bool SP2 = false>
; __device__ __forceinline__ void gemm_phase(PG8_LAS unsigned char* lds, const Gemm g, const Sched& S, const Epi& E) {
;     ...
;             PG8_LDA(At, 1, 1); PG8_STAGE(PG8_SB(1, 0), b3, voffB); PG8_STAGE(PG8_SB(1, 1), b3 + hstepB, voffB); PG8_STAGE(PG8_SA(1, 0), a3, voffA);
;             PG8_WAIT_V(8); PG8_WAIT_L(0); PG8_BAR; PG8_MMA(1, 0, At, B0); PG8_MMA(1, 1, At, B1); PG8_BAR; PG8_SCHED;
;     ...
;         if constexpr (ALIGN_EPI) { if (wr == 0) PG8_BAR; }
	s_add_i32 s10, s12, s67
	v_lshl_add_u64 v[184:185], v[184:185], 0, s[60:61]
	s_mov_b32 m0, s10
	ds_read_b128 v[176:179], v166 offset:49152
	ds_read_b128 v[180:183], v166 offset:50176
	ds_read_b128 v[206:209], v166 offset:51200
	ds_read_b128 v[210:213], v166 offset:52224
	ds_read_b128 v[214:217], v166 offset:53248
	ds_read_b128 v[218:221], v166 offset:54272
	ds_read_b128 v[236:239], v166 offset:55296
	ds_read_b128 v[240:243], v166 offset:56320
	global_load_lds_dwordx4 v[184:185], off
	s_add_i32 m0, s10, 0x2000
	s_add_u32 s10, s46, 0x80080
	v_lshl_add_u64 v[184:185], v[194:195], 0, s[60:61]
	s_addc_u32 s11, s47, 0
	s_add_i32 s12, s13, s67
	global_load_lds_dwordx4 v[184:185], off
	v_lshl_add_u64 v[184:185], s[10:11], 0, v[146:147]
	s_mov_b32 m0, s12
	s_nop 0
	global_load_lds_dwordx4 v[184:185], off
	v_lshl_add_u64 v[184:185], s[10:11], 0, v[142:143]
	s_add_i32 m0, s12, 0x2000
	s_nop 0
	global_load_lds_dwordx4 v[184:185], off
	v_lshl_add_u64 v[184:185], v[196:197], 0, s[60:61]
	s_mov_b32 m0, s82
	s_nop 0
	global_load_lds_dwordx4 v[184:185], off
	v_lshl_add_u64 v[184:185], v[198:199], 0, s[60:61]
	s_mov_b32 m0, s42
	s_nop 0
	global_load_lds_dwordx4 v[184:185], off
	s_waitcnt vmcnt(8)
	s_waitcnt lgkmcnt(0)
	s_barrier
	v_mfma_f32_16x16x32_bf16 v[62:65], v[130:133], v[176:179], v[62:65]
	v_mfma_f32_16x16x32_bf16 v[58:61], v[138:141], v[176:179], v[58:61]
	v_mfma_f32_16x16x32_bf16 v[46:49], v[130:133], v[206:209], v[46:49]
	v_mfma_f32_16x16x32_bf16 v[42:45], v[138:141], v[206:209], v[42:45]
	v_mfma_f32_16x16x32_bf16 v[30:33], v[130:133], v[214:217], v[30:33]
	v_mfma_f32_16x16x32_bf16 v[26:29], v[138:141], v[214:217], v[26:29]
	v_mfma_f32_16x16x32_bf16 v[14:17], v[130:133], v[236:239], v[14:17]
	v_mfma_f32_16x16x32_bf16 v[10:13], v[138:141], v[236:239], v[10:13]
	v_mfma_f32_16x16x32_bf16 v[62:65], v[134:137], v[180:183], v[62:65]
	v_mfma_f32_16x16x32_bf16 v[58:61], v[152:155], v[180:183], v[58:61]
	v_mfma_f32_16x16x32_bf16 v[46:49], v[134:137], v[210:213], v[46:49]
	v_mfma_f32_16x16x32_bf16 v[42:45], v[152:155], v[210:213], v[42:45]
	v_mfma_f32_16x16x32_bf16 v[30:33], v[134:137], v[218:221], v[30:33]
	v_mfma_f32_16x16x32_bf16 v[26:29], v[152:155], v[218:221], v[26:29]
	v_mfma_f32_16x16x32_bf16 v[14:17], v[134:137], v[240:243], v[14:17]
	v_mfma_f32_16x16x32_bf16 v[10:13], v[152:155], v[240:243], v[10:13]
	v_mfma_f32_16x16x32_bf16 v[54:57], v[156:159], v[176:179], v[54:57]
	v_mfma_f32_16x16x32_bf16 v[50:53], v[168:171], v[176:179], v[50:53]
	v_mfma_f32_16x16x32_bf16 v[38:41], v[156:159], v[206:209], v[38:41]
	v_mfma_f32_16x16x32_bf16 v[34:37], v[168:171], v[206:209], v[34:37]
	v_mfma_f32_16x16x32_bf16 v[22:25], v[156:159], v[214:217], v[22:25]
	v_mfma_f32_16x16x32_bf16 v[18:21], v[168:171], v[214:217], v[18:21]
	v_mfma_f32_16x16x32_bf16 v[6:9], v[156:159], v[236:239], v[6:9]
	v_mfma_f32_16x16x32_bf16 v[2:5], v[168:171], v[236:239], v[2:5]
	v_mfma_f32_16x16x32_bf16 v[54:57], v[160:163], v[180:183], v[54:57]
	v_mfma_f32_16x16x32_bf16 v[50:53], v[172:175], v[180:183], v[50:53]
	v_mfma_f32_16x16x32_bf16 v[38:41], v[160:163], v[210:213], v[38:41]
	v_mfma_f32_16x16x32_bf16 v[34:37], v[172:175], v[210:213], v[34:37]
	v_mfma_f32_16x16x32_bf16 v[22:25], v[160:163], v[218:221], v[22:25]
	v_mfma_f32_16x16x32_bf16 v[18:21], v[172:175], v[218:221], v[18:21]
	v_mfma_f32_16x16x32_bf16 v[6:9], v[160:163], v[240:243], v[6:9]
	v_mfma_f32_16x16x32_bf16 v[2:5], v[172:175], v[240:243], v[2:5]
	s_barrier
	s_add_i32 s9, s9, 2
	s_add_u32 s38, s38, 0x100
	s_addc_u32 s39, s39, 0
	s_add_u32 s7, s7, 0x100
	s_addc_u32 s8, s8, 0
	s_cmpk_gt_u32 s9, 0x7d
	s_cbranch_scc0 .LBB0_1071
	s_and_b64 vcc, exec, s[72:73]
	s_cbranch_vccz .LBB0_1074
	s_barrier

; #define PG8_STAGE(bufoff, gbase, voff) do { _Pragma("unroll") for (int _i = 0; _i < 2; ++_i) \
;         __builtin_amdgcn_global_load_lds((const unsigned*)((const char*)(gbase) + (voff)[_i]), (PG8_LAS unsigned*)(lds + (bufoff) + ldsw + _i * 8192), 16, 0, 0); } while (0)
; #define PG8_LDA(dst, b, h) do { _Pragma("unroll") for (int m = 0; m < 4; ++m) _Pragma("unroll") for (int k = 0; k < 2; ++k) dst[m][k] = *(const PG8_LAS bf16x8*)(lds + PG8_SA(b, h) + aoff + m * 2048 + k * 1024); } while (0)
; #define PG8_LDB(dst, b, h) do { _Pragma("unroll") for (int n = 0; n < 2; ++n) _Pragma("unroll") for (int k = 0; k < 2; ++k) dst[n][k] = *(const PG8_LAS bf16x8*)(lds + PG8_SB(b, h) + boff + n * 2048 + k * 1024); } while (0)
; #define PG8_WAIT_V(n) asm volatile("s_waitcnt vmcnt(" #n ")" ::: "memory")
; template <class Epi, class Sched, bool ALIGN_EPI = false, bool SP2 = false>
; __device__ __forceinline__ void gemm_phase(PG8_LAS unsigned char* lds, const Gemm g, const Sched& S, const Epi& E) {
;     ...
;         const char* nA = has_next ? (const char*)g.A + (size_t)nxt.pm * tstep : cA; const char* nB = has_next ? (const char*)g.Bt + (size_t)nxt.pn * tstep : cB;
;         for (int t = 0; t < nt; t += 2) {
;             const bool last = (t == nt - 2);
;             const char* a1 = cA + (size_t)(t + 1) * kstep;
;             const char* a2 = last ? nA : cA + (size_t)(t + 2) * kstep; const char* b2 = last ? nB : cB + (size_t)(t + 2) * kstep;
;             const char* a3 = a2 + kstep; const char* b3 = b2 + kstep;
;             if (last && has_next) S.a_ready(nxt);
;             if constexpr (SP2) {
;             PG8_LDB(B0, 0, 0); PG8_LDB(B1, 0, 1); PG8_SCHED; PG8_LDA(At, 0, 0); PG8_STAGE(PG8_SA(1, 1), a1 + hstep, voffA);
;             PG8_WAIT_V(8); PG8_WAIT_L(0); PG8_BAR; PG8_MMA(0, 0, At, B0); PG8_MMA(0, 1, At, B1); PG8_BAR; PG8_SCHED;
;             PG8_LDA(At, 0, 1); PG8_STAGE(PG8_SB(0, 0), b2, voffB); PG8_STAGE(PG8_SB(0, 1), b2 + hstepB, voffB); PG8_STAGE(PG8_SA(0, 0), a2, voffA);
;             PG8_WAIT_V(8); PG8_WAIT_L(0); PG8_BAR; PG8_MMA(1, 0, At, B0); PG8_MMA(1, 1, At, B1); PG8_BAR; PG8_SCHED;
;             PG8_LDB(B0, 1, 0); PG8_LDB(B1, 1, 1); PG8_SCHED; PG8_LDA(At, 1, 0); PG8_STAGE(PG8_SA(0, 1), a2 + hstep, voffA);
;             PG8_WAIT_V(8); PG8_WAIT_L(0); PG8_BAR; PG8_MMA(0, 0, At, B0); PG8_MMA(0, 1, At, B1); PG8_BAR; PG8_SCHED;
.LBB0_1233:
	s_add_u32 s9, s68, s80
	s_addc_u32 s10, s69, s81
	s_add_u32 s9, s9, 0x100
	s_addc_u32 s10, s10, 0
	s_add_u32 s11, s36, s80
	s_addc_u32 s12, s37, s81
	s_add_i32 s13, 0, 0x10000
	s_cmpk_eq_i32 s80, 0xf00
	s_cselect_b32 s93, s4, s10
	s_cselect_b32 s92, s5, s9
	v_add_u32_e32 v144, s13, v145
	s_cselect_b32 s85, s6, s12
	s_cselect_b32 s84, s7, s11
	s_add_i32 s9, 0, 0x14000
	ds_read_b128 v[152:155], v144
	ds_read_b128 v[156:159], v144 offset:1024
	ds_read_b128 v[160:163], v144 offset:2048
	ds_read_b128 v[164:167], v144 offset:3072
	v_add_u32_e32 v144, s9, v145
	ds_read_b128 v[168:171], v144
	ds_read_b128 v[172:175], v144 offset:1024
	ds_read_b128 v[176:179], v144 offset:2048
	ds_read_b128 v[180:183], v144 offset:3072
	v_lshl_add_u64 v[184:185], v[140:141], 0, s[80:81]
	s_add_i32 m0, s51, 0xc000
	ds_read_b128 v[206:209], v151
	ds_read_b128 v[210:213], v151 offset:1024
	ds_read_b128 v[214:217], v151 offset:2048
	ds_read_b128 v[218:221], v151 offset:3072
	ds_read_b128 v[236:239], v151 offset:4096
	ds_read_b128 v[240:243], v151 offset:5120
	ds_read_b128 v[244:247], v151 offset:6144
	ds_read_b128 v[194:197], v151 offset:7168
	global_load_lds_dwordx4 v[184:185], off
	v_lshl_add_u64 v[184:185], v[142:143], 0, s[80:81]
	s_add_i32 m0, s51, 0xe000
	s_nop 0
	global_load_lds_dwordx4 v[184:185], off
	s_waitcnt vmcnt(8)
	s_waitcnt lgkmcnt(0)
	s_barrier
	v_mfma_f32_16x16x32_bf16 v[126:129], v[152:155], v[206:209], v[126:129]
	v_mfma_f32_16x16x32_bf16 v[122:125], v[160:163], v[206:209], v[122:125]
	v_mfma_f32_16x16x32_bf16 v[118:121], v[152:155], v[214:217], v[118:121]
	v_mfma_f32_16x16x32_bf16 v[114:117], v[160:163], v[214:217], v[114:117]
	v_mfma_f32_16x16x32_bf16 v[110:113], v[152:155], v[236:239], v[110:113]
	v_mfma_f32_16x16x32_bf16 v[106:109], v[160:163], v[236:239], v[106:109]
	v_mfma_f32_16x16x32_bf16 v[102:105], v[152:155], v[244:247], v[102:105]
	v_mfma_f32_16x16x32_bf16 v[98:101], v[160:163], v[244:247], v[98:101]
	v_mfma_f32_16x16x32_bf16 v[126:129], v[156:159], v[210:213], v[126:129]
	v_mfma_f32_16x16x32_bf16 v[122:125], v[164:167], v[210:213], v[122:125]
	v_mfma_f32_16x16x32_bf16 v[118:121], v[156:159], v[218:221], v[118:121]
	v_mfma_f32_16x16x32_bf16 v[114:117], v[164:167], v[218:221], v[114:117]
	v_mfma_f32_16x16x32_bf16 v[110:113], v[156:159], v[240:243], v[110:113]
	v_mfma_f32_16x16x32_bf16 v[106:109], v[164:167], v[240:243], v[106:109]
	v_mfma_f32_16x16x32_bf16 v[102:105], v[156:159], v[194:197], v[102:105]
	v_mfma_f32_16x16x32_bf16 v[98:101], v[164:167], v[194:197], v[98:101]
	v_mfma_f32_16x16x32_bf16 v[94:97], v[168:171], v[206:209], v[94:97]
	v_mfma_f32_16x16x32_bf16 v[90:93], v[176:179], v[206:209], v[90:93]
	v_mfma_f32_16x16x32_bf16 v[86:89], v[168:171], v[214:217], v[86:89]
	v_mfma_f32_16x16x32_bf16 v[82:85], v[176:179], v[214:217], v[82:85]
	v_mfma_f32_16x16x32_bf16 v[78:81], v[168:171], v[236:239], v[78:81]
	v_mfma_f32_16x16x32_bf16 v[74:77], v[176:179], v[236:239], v[74:77]
	v_mfma_f32_16x16x32_bf16 v[70:73], v[168:171], v[244:247], v[70:73]
	v_mfma_f32_16x16x32_bf16 v[66:69], v[176:179], v[244:247], v[66:69]
	v_mfma_f32_16x16x32_bf16 v[94:97], v[172:175], v[210:213], v[94:97]
	v_mfma_f32_16x16x32_bf16 v[90:93], v[180:183], v[210:213], v[90:93]
	v_mfma_f32_16x16x32_bf16 v[86:89], v[172:175], v[218:221], v[86:89]
	v_mfma_f32_16x16x32_bf16 v[82:85], v[180:183], v[218:221], v[82:85]
	v_mfma_f32_16x16x32_bf16 v[78:81], v[172:175], v[240:243], v[78:81]
	v_mfma_f32_16x16x32_bf16 v[74:77], v[180:183], v[240:243], v[74:77]
	v_mfma_f32_16x16x32_bf16 v[70:73], v[172:175], v[194:197], v[70:73]
	v_mfma_f32_16x16x32_bf16 v[66:69], v[180:183], v[194:197], v[66:69]
	s_barrier
	s_add_i32 s10, s13, s42
	v_lshl_add_u64 v[184:185], s[84:85], 0, v[130:131]
	s_mov_b32 m0, s10
	ds_read_b128 v[194:197], v151 offset:16384
	ds_read_b128 v[206:209], v151 offset:17408
	ds_read_b128 v[210:213], v151 offset:18432
	ds_read_b128 v[214:217], v151 offset:19456
	ds_read_b128 v[218:221], v151 offset:20480
	ds_read_b128 v[236:239], v151 offset:21504
	ds_read_b128 v[240:243], v151 offset:22528
	ds_read_b128 v[244:247], v151 offset:23552
	global_load_lds_dwordx4 v[184:185], off
	s_add_i32 m0, s10, 0x2000
	s_add_u32 s10, s84, 0x20000
	v_lshl_add_u64 v[198:199], s[84:85], 0, v[134:135]
	s_addc_u32 s11, s85, 0
	s_add_i32 s9, s9, s42
	global_load_lds_dwordx4 v[198:199], off
	v_lshl_add_u64 v[222:223], s[10:11], 0, v[130:131]
	s_mov_b32 m0, s9
	v_lshl_add_u64 v[234:235], s[92:93], 0, v[132:133]
	global_load_lds_dwordx4 v[222:223], off
	v_lshl_add_u64 v[222:223], s[10:11], 0, v[134:135]
	s_add_i32 m0, s9, 0x2000
	s_nop 0
	global_load_lds_dwordx4 v[222:223], off
	v_lshl_add_u64 v[222:223], s[92:93], 0, v[190:191]
	s_mov_b32 m0, s51
	s_nop 0
	global_load_lds_dwordx4 v[222:223], off
	s_mov_b32 m0, s67
	s_nop 0
	global_load_lds_dwordx4 v[234:235], off
	s_waitcnt vmcnt(8)
	s_waitcnt lgkmcnt(0)
	s_barrier
; #define PG8_STAGE(bufoff, gbase, voff) do { _Pragma("unroll") for (int _i = 0; _i < 2; ++_i) \
;         __builtin_amdgcn_global_load_lds((const unsigned*)((const char*)(gbase) + (voff)[_i]), (PG8_LAS unsigned*)(lds + (bufoff) + ldsw + _i * 8192), 16, 0, 0); } while (0)
; #define PG8_LDA(dst, b, h) do { _Pragma("unroll") for (int m = 0; m < 4; ++m) _Pragma("unroll") for (int k = 0; k < 2; ++k) dst[m][k] = *(const PG8_LAS bf16x8*)(lds + PG8_SA(b, h) + aoff + m * 2048 + k * 1024); } while (0)
; #define PG8_LDB(dst, b, h) do { _Pragma("unroll") for (int n = 0; n < 2; ++n) _Pragma("unroll") for (int k = 0; k < 2; ++k) dst[n][k] = *(const PG8_LAS bf16x8*)(lds + PG8_SB(b, h) + boff + n * 2048 + k * 1024); } while (0)
; #define PG8_MMA(ai, bj, At, Bt) do { __builtin_amdgcn_s_setprio(1); _Pragma("unroll") for (int m = 0; m < 4; ++m) _Pragma("unroll") for (int n = 0; n < 2; ++n) _Pragma("unroll") for (int k = 0; k < 2; ++k) \
;         acc[ai][bj][m][n] = __builtin_amdgcn_mfma_f32_16x16x32_bf16(Bt[n][k], At[m][k], acc[ai][bj][m][n], 0, 0, 0); __builtin_amdgcn_s_setprio(0); } while (0)
; #define PG8_WAIT_V(n) asm volatile("s_waitcnt vmcnt(" #n ")" ::: "memory")
; #define PG8_WAIT_L(n) asm volatile("s_waitcnt lgkmcnt(" #n ")" ::: "memory")
; #define PG8_BAR __builtin_amdgcn_s_barrier()
; #define PG8_SCHED __builtin_amdgcn_sched_barrier(0)
; template <class Epi, class Sched, bool ALIGN_EPI = false, bool SP2 = false>
; __device__ __forceinline__ void gemm_phase(PG8_LAS unsigned char* lds, const Gemm g, const Sched& S, const Epi& E) {
;     ...
;             PG8_WAIT_V(8); PG8_WAIT_L(0); PG8_BAR; PG8_MMA(1, 0, At, B0); PG8_MMA(1, 1, At, B1); PG8_BAR; PG8_SCHED;
;             PG8_LDB(B0, 1, 0); PG8_LDB(B1, 1, 1); PG8_SCHED; PG8_LDA(At, 1, 0); PG8_STAGE(PG8_SA(0, 1), a2 + hstep, voffA);
;             PG8_WAIT_V(8); PG8_WAIT_L(0); PG8_BAR; PG8_MMA(0, 0, At, B0); PG8_MMA(0, 1, At, B1); PG8_BAR; PG8_SCHED;
	v_mfma_f32_16x16x32_bf16 v[62:65], v[152:155], v[194:197], v[62:65]
	v_mfma_f32_16x16x32_bf16 v[58:61], v[160:163], v[194:197], v[58:61]
	v_mfma_f32_16x16x32_bf16 v[54:57], v[152:155], v[210:213], v[54:57]
	v_mfma_f32_16x16x32_bf16 v[50:53], v[160:163], v[210:213], v[50:53]
	v_mfma_f32_16x16x32_bf16 v[46:49], v[152:155], v[218:221], v[46:49]
	v_mfma_f32_16x16x32_bf16 v[42:45], v[160:163], v[218:221], v[42:45]
	v_mfma_f32_16x16x32_bf16 v[38:41], v[152:155], v[240:243], v[38:41]
	v_mfma_f32_16x16x32_bf16 v[34:37], v[160:163], v[240:243], v[34:37]
	v_mfma_f32_16x16x32_bf16 v[62:65], v[156:159], v[206:209], v[62:65]
	v_mfma_f32_16x16x32_bf16 v[58:61], v[164:167], v[206:209], v[58:61]
	v_mfma_f32_16x16x32_bf16 v[54:57], v[156:159], v[214:217], v[54:57]
	v_mfma_f32_16x16x32_bf16 v[50:53], v[164:167], v[214:217], v[50:53]
	v_mfma_f32_16x16x32_bf16 v[46:49], v[156:159], v[236:239], v[46:49]
	v_mfma_f32_16x16x32_bf16 v[42:45], v[164:167], v[236:239], v[42:45]
	v_mfma_f32_16x16x32_bf16 v[38:41], v[156:159], v[244:247], v[38:41]
	v_mfma_f32_16x16x32_bf16 v[34:37], v[164:167], v[244:247], v[34:37]
	v_mfma_f32_16x16x32_bf16 v[30:33], v[168:171], v[194:197], v[30:33]
	v_mfma_f32_16x16x32_bf16 v[26:29], v[176:179], v[194:197], v[26:29]
	v_mfma_f32_16x16x32_bf16 v[22:25], v[168:171], v[210:213], v[22:25]
	v_mfma_f32_16x16x32_bf16 v[18:21], v[176:179], v[210:213], v[18:21]
	v_mfma_f32_16x16x32_bf16 v[14:17], v[168:171], v[218:221], v[14:17]
	v_mfma_f32_16x16x32_bf16 v[10:13], v[176:179], v[218:221], v[10:13]
	v_mfma_f32_16x16x32_bf16 v[6:9], v[168:171], v[240:243], v[6:9]
	v_mfma_f32_16x16x32_bf16 v[2:5], v[176:179], v[240:243], v[2:5]
	v_mfma_f32_16x16x32_bf16 v[30:33], v[172:175], v[206:209], v[30:33]
	v_mfma_f32_16x16x32_bf16 v[26:29], v[180:183], v[206:209], v[26:29]
	v_mfma_f32_16x16x32_bf16 v[22:25], v[172:175], v[214:217], v[22:25]
	v_mfma_f32_16x16x32_bf16 v[18:21], v[180:183], v[214:217], v[18:21]
	v_mfma_f32_16x16x32_bf16 v[14:17], v[172:175], v[236:239], v[14:17]
	v_mfma_f32_16x16x32_bf16 v[10:13], v[180:183], v[236:239], v[10:13]
	v_mfma_f32_16x16x32_bf16 v[6:9], v[172:175], v[244:247], v[6:9]
	v_mfma_f32_16x16x32_bf16 v[2:5], v[180:183], v[244:247], v[2:5]
	s_barrier
	s_add_i32 s9, 0, 0x18000
	v_add_u32_e32 v144, s9, v145
	s_add_i32 s12, 0, 0x1c000
	ds_read_b128 v[152:155], v144
	ds_read_b128 v[156:159], v144 offset:1024
	ds_read_b128 v[160:163], v144 offset:2048
	ds_read_b128 v[164:167], v144 offset:3072
	v_add_u32_e32 v144, s12, v145
	ds_read_b128 v[168:171], v144
	ds_read_b128 v[172:175], v144 offset:1024
	ds_read_b128 v[176:179], v144 offset:2048
	ds_read_b128 v[180:183], v144 offset:3072
	s_add_u32 s10, s92, 0x80000
	s_addc_u32 s11, s93, 0
	s_mov_b32 m0, s74
	v_lshl_add_u64 v[186:187], s[10:11], 0, v[190:191]
	ds_read_b128 v[194:197], v151 offset:32768
	ds_read_b128 v[206:209], v151 offset:33792
	ds_read_b128 v[210:213], v151 offset:34816
	ds_read_b128 v[214:217], v151 offset:35840
	ds_read_b128 v[218:221], v151 offset:36864
	ds_read_b128 v[236:239], v151 offset:37888
	ds_read_b128 v[240:243], v151 offset:38912
	ds_read_b128 v[244:247], v151 offset:39936
	global_load_lds_dwordx4 v[186:187], off
	v_lshl_add_u64 v[186:187], s[10:11], 0, v[132:133]
	s_mov_b32 m0, s75
	s_nop 0
	global_load_lds_dwordx4 v[186:187], off
	s_waitcnt vmcnt(8)
	s_waitcnt lgkmcnt(0)
	s_barrier
	v_mfma_f32_16x16x32_bf16 v[126:129], v[152:155], v[194:197], v[126:129]
	v_mfma_f32_16x16x32_bf16 v[122:125], v[160:163], v[194:197], v[122:125]
	v_mfma_f32_16x16x32_bf16 v[118:121], v[152:155], v[210:213], v[118:121]
	v_mfma_f32_16x16x32_bf16 v[114:117], v[160:163], v[210:213], v[114:117]
	v_mfma_f32_16x16x32_bf16 v[110:113], v[152:155], v[218:221], v[110:113]
	v_mfma_f32_16x16x32_bf16 v[106:109], v[160:163], v[218:221], v[106:109]
	v_mfma_f32_16x16x32_bf16 v[102:105], v[152:155], v[240:243], v[102:105]
	v_mfma_f32_16x16x32_bf16 v[98:101], v[160:163], v[240:243], v[98:101]
	v_mfma_f32_16x16x32_bf16 v[126:129], v[156:159], v[206:209], v[126:129]
	v_mfma_f32_16x16x32_bf16 v[122:125], v[164:167], v[206:209], v[122:125]
	v_mfma_f32_16x16x32_bf16 v[118:121], v[156:159], v[214:217], v[118:121]
	v_mfma_f32_16x16x32_bf16 v[114:117], v[164:167], v[214:217], v[114:117]
	v_mfma_f32_16x16x32_bf16 v[110:113], v[156:159], v[236:239], v[110:113]
	v_mfma_f32_16x16x32_bf16 v[106:109], v[164:167], v[236:239], v[106:109]
	v_mfma_f32_16x16x32_bf16 v[102:105], v[156:159], v[244:247], v[102:105]
	v_mfma_f32_16x16x32_bf16 v[98:101], v[164:167], v[244:247], v[98:101]
	v_mfma_f32_16x16x32_bf16 v[94:97], v[168:171], v[194:197], v[94:97]
	v_mfma_f32_16x16x32_bf16 v[90:93], v[176:179], v[194:197], v[90:93]
	v_mfma_f32_16x16x32_bf16 v[86:89], v[168:171], v[210:213], v[86:89]
	v_mfma_f32_16x16x32_bf16 v[82:85], v[176:179], v[210:213], v[82:85]
	v_mfma_f32_16x16x32_bf16 v[78:81], v[168:171], v[218:221], v[78:81]
	v_mfma_f32_16x16x32_bf16 v[74:77], v[176:179], v[218:221], v[74:77]
	v_mfma_f32_16x16x32_bf16 v[70:73], v[168:171], v[240:243], v[70:73]
	v_mfma_f32_16x16x32_bf16 v[66:69], v[176:179], v[240:243], v[66:69]
	v_mfma_f32_16x16x32_bf16 v[94:97], v[172:175], v[206:209], v[94:97]
	v_mfma_f32_16x16x32_bf16 v[90:93], v[180:183], v[206:209], v[90:93]
	v_mfma_f32_16x16x32_bf16 v[86:89], v[172:175], v[214:217], v[86:89]
	v_mfma_f32_16x16x32_bf16 v[82:85], v[180:183], v[214:217], v[82:85]
	v_mfma_f32_16x16x32_bf16 v[78:81], v[172:175], v[236:239], v[78:81]
	v_mfma_f32_16x16x32_bf16 v[74:77], v[180:183], v[236:239], v[74:77]
	v_mfma_f32_16x16x32_bf16 v[70:73], v[172:175], v[244:247], v[70:73]
	v_mfma_f32_16x16x32_bf16 v[66:69], v[180:183], v[244:247], v[66:69]
	s_barrier
; #define PG8_STAGE(bufoff, gbase, voff) do { _Pragma("unroll") for (int _i = 0; _i < 2; ++_i) \
;         __builtin_amdgcn_global_load_lds((const unsigned*)((const char*)(gbase) + (voff)[_i]), (PG8_LAS unsigned*)(lds + (bufoff) + ldsw + _i * 8192), 16, 0, 0); } while (0)
; #define PG8_LDA(dst, b, h) do { _Pragma("unroll") for (int m = 0; m < 4; ++m) _Pragma("unroll") for (int k = 0; k < 2; ++k) dst[m][k] = *(const PG8_LAS bf16x8*)(lds + PG8_SA(b, h) + aoff + m * 2048 + k * 1024); } while (0)
; #define PG8_MMA(ai, bj, At, Bt) do { __builtin_amdgcn_s_setprio(1); _Pragma("unroll") for (int m = 0; m < 4; ++m) _Pragma("unroll") for (int n = 0; n < 2; ++n) _Pragma("unroll") for (int k = 0; k < 2; ++k) \
;         acc[ai][bj][m][n] = __builtin_amdgcn_mfma_f32_16x16x32_bf16(Bt[n][k], At[m][k], acc[ai][bj][m][n], 0, 0, 0); __builtin_amdgcn_s_setprio(0); } while (0)
; #define PG8_WAIT_V(n) asm volatile("s_waitcnt vmcnt(" #n ")" ::: "memory")
; #define PG8_WAIT_L(n) asm volatile("s_waitcnt lgkmcnt(" #n ")" ::: "memory")
; #define PG8_BAR __builtin_amdgcn_s_barrier()
; #define PG8_SCHED __builtin_amdgcn_sched_barrier(0)
; template <class Epi, class Sched, bool ALIGN_EPI = false, bool SP2 = false>
; __device__ __forceinline__ void gemm_phase(PG8_LAS unsigned char* lds, const Gemm g, const Sched& S, const Epi& E) {
;     ...
;             PG8_LDA(At, 1, 1); PG8_STAGE(PG8_SB(1, 0), b3, voffB); PG8_STAGE(PG8_SB(1, 1), b3 + hstepB, voffB); PG8_STAGE(PG8_SA(1, 0), a3, voffA);
;             PG8_WAIT_V(8); PG8_WAIT_L(0); PG8_BAR; PG8_MMA(1, 0, At, B0); PG8_MMA(1, 1, At, B1); PG8_BAR; PG8_SCHED;
;     ...
;         if constexpr (ALIGN_EPI) { if (wr == 0) PG8_BAR; }
	s_add_i32 s9, s9, s42
	v_lshl_add_u64 v[184:185], v[184:185], 0, s[60:61]
	s_mov_b32 m0, s9
	ds_read_b128 v[194:197], v151 offset:49152
	ds_read_b128 v[206:209], v151 offset:50176
	ds_read_b128 v[210:213], v151 offset:51200
	ds_read_b128 v[214:217], v151 offset:52224
	ds_read_b128 v[218:221], v151 offset:53248
	ds_read_b128 v[236:239], v151 offset:54272
	ds_read_b128 v[240:243], v151 offset:55296
	ds_read_b128 v[244:247], v151 offset:56320
	global_load_lds_dwordx4 v[184:185], off
	s_add_i32 m0, s9, 0x2000
	s_add_u32 s10, s84, 0x20080
	v_lshl_add_u64 v[184:185], v[198:199], 0, s[60:61]
	s_addc_u32 s11, s85, 0
	s_add_i32 s9, s12, s42
	global_load_lds_dwordx4 v[184:185], off
	v_lshl_add_u64 v[184:185], s[10:11], 0, v[130:131]
	s_mov_b32 m0, s9
	s_nop 0
	global_load_lds_dwordx4 v[184:185], off
	v_lshl_add_u64 v[184:185], s[10:11], 0, v[134:135]
	s_add_i32 m0, s9, 0x2000
	s_nop 0
	global_load_lds_dwordx4 v[184:185], off
	v_lshl_add_u64 v[184:185], v[222:223], 0, s[60:61]
	s_mov_b32 m0, s82
	s_nop 0
	global_load_lds_dwordx4 v[184:185], off
	v_lshl_add_u64 v[184:185], v[234:235], 0, s[60:61]
	s_mov_b32 m0, s86
	s_nop 0
	global_load_lds_dwordx4 v[184:185], off
	s_waitcnt vmcnt(8)
	s_waitcnt lgkmcnt(0)
	s_barrier
	v_mfma_f32_16x16x32_bf16 v[62:65], v[152:155], v[194:197], v[62:65]
	v_mfma_f32_16x16x32_bf16 v[58:61], v[160:163], v[194:197], v[58:61]
	v_mfma_f32_16x16x32_bf16 v[54:57], v[152:155], v[210:213], v[54:57]
	v_mfma_f32_16x16x32_bf16 v[50:53], v[160:163], v[210:213], v[50:53]
	v_mfma_f32_16x16x32_bf16 v[46:49], v[152:155], v[218:221], v[46:49]
	v_mfma_f32_16x16x32_bf16 v[42:45], v[160:163], v[218:221], v[42:45]
	v_mfma_f32_16x16x32_bf16 v[38:41], v[152:155], v[240:243], v[38:41]
	v_mfma_f32_16x16x32_bf16 v[34:37], v[160:163], v[240:243], v[34:37]
	v_mfma_f32_16x16x32_bf16 v[62:65], v[156:159], v[206:209], v[62:65]
	v_mfma_f32_16x16x32_bf16 v[58:61], v[164:167], v[206:209], v[58:61]
	v_mfma_f32_16x16x32_bf16 v[54:57], v[156:159], v[214:217], v[54:57]
	v_mfma_f32_16x16x32_bf16 v[50:53], v[164:167], v[214:217], v[50:53]
	v_mfma_f32_16x16x32_bf16 v[46:49], v[156:159], v[236:239], v[46:49]
	v_mfma_f32_16x16x32_bf16 v[42:45], v[164:167], v[236:239], v[42:45]
	v_mfma_f32_16x16x32_bf16 v[38:41], v[156:159], v[244:247], v[38:41]
	v_mfma_f32_16x16x32_bf16 v[34:37], v[164:167], v[244:247], v[34:37]
	v_mfma_f32_16x16x32_bf16 v[30:33], v[168:171], v[194:197], v[30:33]
	v_mfma_f32_16x16x32_bf16 v[26:29], v[176:179], v[194:197], v[26:29]
	v_mfma_f32_16x16x32_bf16 v[22:25], v[168:171], v[210:213], v[22:25]
	v_mfma_f32_16x16x32_bf16 v[18:21], v[176:179], v[210:213], v[18:21]
	v_mfma_f32_16x16x32_bf16 v[14:17], v[168:171], v[218:221], v[14:17]
	v_mfma_f32_16x16x32_bf16 v[10:13], v[176:179], v[218:221], v[10:13]
	v_mfma_f32_16x16x32_bf16 v[6:9], v[168:171], v[240:243], v[6:9]
	v_mfma_f32_16x16x32_bf16 v[2:5], v[176:179], v[240:243], v[2:5]
	v_mfma_f32_16x16x32_bf16 v[30:33], v[172:175], v[206:209], v[30:33]
	v_mfma_f32_16x16x32_bf16 v[26:29], v[180:183], v[206:209], v[26:29]
	v_mfma_f32_16x16x32_bf16 v[22:25], v[172:175], v[214:217], v[22:25]
	v_mfma_f32_16x16x32_bf16 v[18:21], v[180:183], v[214:217], v[18:21]
	v_mfma_f32_16x16x32_bf16 v[14:17], v[172:175], v[236:239], v[14:17]
	v_mfma_f32_16x16x32_bf16 v[10:13], v[180:183], v[236:239], v[10:13]
	v_mfma_f32_16x16x32_bf16 v[6:9], v[172:175], v[244:247], v[6:9]
	v_mfma_f32_16x16x32_bf16 v[2:5], v[180:183], v[244:247], v[2:5]
	s_barrier
	s_add_i32 s8, s8, 2
	s_add_u32 s80, s80, 0x100
	s_addc_u32 s81, s81, 0
	s_cmp_gt_u32 s8, 29
	s_cbranch_scc0 .LBB0_1233
	s_and_b64 vcc, exec, s[62:63]
	s_cbranch_vccz .LBB0_1236
	s_barrier
